# the other sample-row split-K GEMMs (P1/P11 gate+up, P4, P9; K=1024): whole-line wave loads, all loads in flight, MFMA fragments through a per-wave LDS staging area
# speedup vs baseline: 1.0255x; 1.0123x over previous
; template <int MODE>
; __device__ __forceinline__ void small_gemm(LAS unsigned char* lds, const bf16* A, const bf16* Bt, int N, int K, bf16* O, int ldc, int act_cols, const float* bias, const bf16* Yv, int ldy, int it0, int it1) {
;     ...
;     for (int it = it0; it < it1; ++it) {
;         const int item = BX + it * GSZ; if (item >= nitems) break;
;         const int rt = item & 3, ct = item >> 2;
;         const int hc = 32 * ct + tl;
;         const int brow = (MODE == 3) ? (256 * (hc >> 7) + (hc & 127)) : hc;
;         const bf16* ap = A + (size_t)(32 * rt + tl) * K + wave * kw + 8 * hh;
;         const bf16* bp = Bt + (size_t)brow * K + wave * kw + 8 * hh;
;         v16f acc0, acc1;
; #pragma unroll
;         for (int r = 0; r < 16; ++r) { acc0[r] = 0.f; acc1[r] = 0.f; }
; #pragma unroll 4
;         for (int ks = 0; ks < nks; ++ks) {
;             const bfx8 a = *(const bfx8*)(ap + 16 * ks);
;             const bfx8 b0 = *(const bfx8*)(bp + 16 * ks);
;             acc0 = __builtin_amdgcn_mfma_f32_32x32x16_bf16(b0, a, acc0, 0, 0, 0);
;             if (MODE == 3) { const bfx8 b1 = *(const bfx8*)(bp + (size_t)128 * K + 16 * ks); acc1 = __builtin_amdgcn_mfma_f32_32x32x16_bf16(b1, a, acc1, 0, 0, 0); }
;         }
.LBB0_201:
	v_and_b32_e32 v70, 63, v182
	v_lshrrev_b32_e32 v71, 6, v182
	s_nop 0
	v_readfirstlane_b32 s98, v71
	s_mul_i32 m0, s98, 0x2400
	s_add_i32 m0, m0, 0x10000
	v_lshrrev_b32_e32 v71, 3, v70
	v_and_b32_e32 v74, 7, v70
	v_lshlrev_b32_e32 v74, 4, v74
	v_mul_u32_u24_e32 v72, 0x90, v71
	v_add3_u32 v72, v72, v74, m0
	v_mul_u32_u24_e32 v73, 0x90, v42
	v_lshrrev_b32_e32 v76, 5, v70
	v_lshl_add_u32 v73, v76, 4, v73
	v_add_u32_e32 v73, m0, v73
	v_lshlrev_b32_e32 v76, 4, v76
	v_sub_u32_e32 v76, v74, v76
	v_sub_u32_e32 v71, v71, v42
	v_lshl_add_u32 v76, v71, 11, v76
	v_ashrrev_i32_e32 v77, 31, v76
	v_lshl_add_u64 v[78:79], v[38:39], 0, v[76:77]
	v_add_co_u32_e32 v54, vcc, s13, v78
	s_nop 1
	v_addc_co_u32_e32 v55, vcc, 0, v79, vcc
	v_add_co_u32_e32 v62, vcc, s14, v78
	s_nop 1
	v_addc_co_u32_e32 v63, vcc, 0, v79, vcc
	v_subrev_u32_e32 v76, 64, v76
	v_ashrrev_i32_e32 v77, 31, v76
	v_lshl_add_u64 v[46:47], v[40:41], 0, v[76:77]
	s_mov_b32 s100, 0x4000
	s_mov_b32 s101, 0
	v_lshl_add_u64 v[48:49], v[46:47], 0, s[100:101]
	v_lshl_add_u64 v[50:51], v[48:49], 0, s[100:101]
	v_lshl_add_u64 v[52:53], v[50:51], 0, s[100:101]
	v_lshl_add_u64 v[56:57], v[54:55], 0, s[100:101]
	v_lshl_add_u64 v[58:59], v[56:57], 0, s[100:101]
	v_lshl_add_u64 v[60:61], v[58:59], 0, s[100:101]
	v_lshl_add_u64 v[64:65], v[62:63], 0, s[100:101]
	v_lshl_add_u64 v[66:67], v[64:65], 0, s[100:101]
	v_lshl_add_u64 v[68:69], v[66:67], 0, s[100:101]
	global_load_dwordx4 v[80:83], v[46:47], off
	global_load_dwordx4 v[84:87], v[48:49], off
	global_load_dwordx4 v[88:91], v[50:51], off
	global_load_dwordx4 v[92:95], v[52:53], off
	global_load_dwordx4 v[96:99], v[54:55], off
	global_load_dwordx4 v[100:103], v[56:57], off
	global_load_dwordx4 v[104:107], v[58:59], off
	global_load_dwordx4 v[108:111], v[60:61], off
	global_load_dwordx4 v[112:115], v[62:63], off
	global_load_dwordx4 v[116:119], v[64:65], off
	global_load_dwordx4 v[120:123], v[66:67], off
	global_load_dwordx4 v[124:127], v[68:69], off
	global_load_dwordx4 v[128:131], v[46:47], off offset:128
	global_load_dwordx4 v[132:135], v[48:49], off offset:128
	global_load_dwordx4 v[136:139], v[50:51], off offset:128
	global_load_dwordx4 v[140:143], v[52:53], off offset:128
	global_load_dwordx4 v[144:147], v[54:55], off offset:128
	global_load_dwordx4 v[148:151], v[56:57], off offset:128
	global_load_dwordx4 v[152:155], v[58:59], off offset:128
	global_load_dwordx4 v[156:159], v[60:61], off offset:128
	global_load_dwordx4 v[160:163], v[62:63], off offset:128
	global_load_dwordx4 v[164:167], v[64:65], off offset:128
	global_load_dwordx4 v[168:171], v[66:67], off offset:128
	global_load_dwordx4 v[172:175], v[68:69], off offset:128
	s_waitcnt vmcnt(12)
	ds_write_b128 v72, v[80:83]
	ds_write_b128 v72, v[84:87] offset:1152
	ds_write_b128 v72, v[88:91] offset:2304
	ds_write_b128 v72, v[92:95] offset:3456
	ds_write_b128 v72, v[96:99] offset:4608
	ds_write_b128 v72, v[100:103] offset:5760
	ds_write_b128 v72, v[104:107] offset:6912
	ds_write_b128 v72, v[108:111] offset:8064
	s_waitcnt lgkmcnt(0)
	ds_read_b128 v[192:195], v73
	ds_read_b128 v[208:211], v73 offset:4608
	ds_read_b128 v[196:199], v73 offset:32
	ds_read_b128 v[212:215], v73 offset:4640
	ds_read_b128 v[200:203], v73 offset:64
	ds_read_b128 v[216:219], v73 offset:4672
	ds_read_b128 v[204:207], v73 offset:96
	ds_read_b128 v[220:223], v73 offset:4704
	s_waitcnt lgkmcnt(6)
	v_mfma_f32_32x32x16_bf16 v[0:15], v[208:211], v[192:195], v[0:15]
	s_waitcnt lgkmcnt(4)
	v_mfma_f32_32x32x16_bf16 v[0:15], v[212:215], v[196:199], v[0:15]
	s_waitcnt lgkmcnt(2)
	v_mfma_f32_32x32x16_bf16 v[0:15], v[216:219], v[200:203], v[0:15]
	s_waitcnt lgkmcnt(0)
	v_mfma_f32_32x32x16_bf16 v[0:15], v[220:223], v[204:207], v[0:15]
	ds_write_b128 v72, v[112:115] offset:4608
	ds_write_b128 v72, v[116:119] offset:5760
	ds_write_b128 v72, v[120:123] offset:6912
	ds_write_b128 v72, v[124:127] offset:8064
	s_waitcnt lgkmcnt(0)
	ds_read_b128 v[208:211], v73 offset:4608
	ds_read_b128 v[212:215], v73 offset:4640
	ds_read_b128 v[216:219], v73 offset:4672
	ds_read_b128 v[220:223], v73 offset:4704
	s_waitcnt lgkmcnt(3)
	v_mfma_f32_32x32x16_bf16 v[16:31], v[208:211], v[192:195], v[16:31]
	s_waitcnt lgkmcnt(2)
	v_mfma_f32_32x32x16_bf16 v[16:31], v[212:215], v[196:199], v[16:31]
	s_waitcnt lgkmcnt(1)
	v_mfma_f32_32x32x16_bf16 v[16:31], v[216:219], v[200:203], v[16:31]
	s_waitcnt lgkmcnt(0)
	v_mfma_f32_32x32x16_bf16 v[16:31], v[220:223], v[204:207], v[16:31]
	s_waitcnt vmcnt(0)
	s_waitcnt lgkmcnt(0)
	ds_write_b128 v72, v[128:131]
	ds_write_b128 v72, v[132:135] offset:1152
	ds_write_b128 v72, v[136:139] offset:2304
	ds_write_b128 v72, v[140:143] offset:3456
	ds_write_b128 v72, v[144:147] offset:4608
	ds_write_b128 v72, v[148:151] offset:5760
	ds_write_b128 v72, v[152:155] offset:6912
	ds_write_b128 v72, v[156:159] offset:8064
	s_waitcnt lgkmcnt(0)
	ds_read_b128 v[192:195], v73
	ds_read_b128 v[208:211], v73 offset:4608
	ds_read_b128 v[196:199], v73 offset:32
	ds_read_b128 v[212:215], v73 offset:4640
	ds_read_b128 v[200:203], v73 offset:64
	ds_read_b128 v[216:219], v73 offset:4672
	ds_read_b128 v[204:207], v73 offset:96
	ds_read_b128 v[220:223], v73 offset:4704
	s_waitcnt lgkmcnt(6)
	v_mfma_f32_32x32x16_bf16 v[0:15], v[208:211], v[192:195], v[0:15]
	s_waitcnt lgkmcnt(4)
	v_mfma_f32_32x32x16_bf16 v[0:15], v[212:215], v[196:199], v[0:15]
	s_waitcnt lgkmcnt(2)
	v_mfma_f32_32x32x16_bf16 v[0:15], v[216:219], v[200:203], v[0:15]
	s_waitcnt lgkmcnt(0)
	v_mfma_f32_32x32x16_bf16 v[0:15], v[220:223], v[204:207], v[0:15]
	ds_write_b128 v72, v[160:163] offset:4608
	ds_write_b128 v72, v[164:167] offset:5760
	ds_write_b128 v72, v[168:171] offset:6912
	ds_write_b128 v72, v[172:175] offset:8064
	s_waitcnt lgkmcnt(0)
	ds_read_b128 v[208:211], v73 offset:4608
	ds_read_b128 v[212:215], v73 offset:4640
	ds_read_b128 v[216:219], v73 offset:4672
	ds_read_b128 v[220:223], v73 offset:4704
	s_waitcnt lgkmcnt(3)
	v_mfma_f32_32x32x16_bf16 v[16:31], v[208:211], v[192:195], v[16:31]
	s_waitcnt lgkmcnt(2)
	v_mfma_f32_32x32x16_bf16 v[16:31], v[212:215], v[196:199], v[16:31]
	s_waitcnt lgkmcnt(1)
	v_mfma_f32_32x32x16_bf16 v[16:31], v[216:219], v[200:203], v[16:31]
	s_waitcnt lgkmcnt(0)
	v_mfma_f32_32x32x16_bf16 v[16:31], v[220:223], v[204:207], v[16:31]
	s_movk_i32 s8, 0x100
	s_barrier
; __device__ __forceinline__ unsigned cvt_pk_bf16(float lo, float hi) { unsigned r; asm volatile("v_cvt_pk_bf16_f32 %0, %1, %2" : "=v"(r) : "v"(lo), "v"(hi)); return r; }
; __device__ __forceinline__ float bf_lo(unsigned w) { return __uint_as_float(w << 16); }
; __device__ __forceinline__ float bf_hi(unsigned w) { return __uint_as_float(w & 0xffff0000u); }
; __device__ __forceinline__ float gelu_t(float x) { const float u = 1.5957691216057308f * (x + 0.044715f * x * x * x); return x * sigmoid_f(u); }
; __device__ __forceinline__ float sigmoid_f(float x) { return __builtin_amdgcn_rcpf(1.0f + __expf(-x)); }
; __device__ __forceinline__ float silu_f(float x) { return x * sigmoid_f(x); }
; template <int MODE>
; __device__ __forceinline__ void small_gemm(LAS unsigned char* lds, const bf16* A, const bf16* Bt, int N, int K, bf16* O, int ldc, int act_cols, const float* bias, const bf16* Yv, int ldy, int it0, int it1) {
;     ...
;         __syncthreads();
; #pragma unroll
;         for (int r = 0; r < 16; ++r) { red[(wave * 16 + r) * 64 + lane] = acc0[r]; if (MODE == 3) red[8192 + (wave * 16 + r) * 64 + lane] = acc1[r]; }
;         __syncthreads();
;         float v0[2], v1[2];
; #pragma unroll
;         for (int e = 0; e < 2; ++e) { float s0 = 0.f, s1 = 0.f;
; #pragma unroll
;             for (int w = 0; w < 8; ++w) { s0 += red[(w * 16 + 2 * wave + e) * 64 + lane]; if (MODE == 3) s1 += red[8192 + (w * 16 + 2 * wave + e) * 64 + lane]; }
;             v0[e] = s0; v1[e] = s1; }
;         const int reg = 2 * wave;
;         const int col = 32 * ct + (reg & 3) + 8 * (reg >> 2) + 4 * hh;
;         const size_t row = (size_t)(32 * rt + tl);
;         float o0 = v0[0], o1 = v0[1];
;         if (MODE == 1) { if (col < act_cols) { o0 = gelu_t(o0); o1 = gelu_t(o1); } }
;         if (MODE == 2) { const unsigned y = *(const unsigned*)(Yv + row * ldy + col); o0 = bf_lo(y) * pg8::sigmoid_f(o0 + bias[col]); o1 = bf_hi(y) * pg8::sigmoid_f(o1 + bias[col + 1]); }
;         if (MODE == 3) { o0 = pg8::silu_f(o0) * v1[0]; o1 = pg8::silu_f(o1) * v1[1]; }
;         *(unsigned*)(O + row * ldc + col) = cvt_pk_bf16(o0, o1);
	s_nop 7
	ds_write2st64_b32 v45, v0, v1 offset1:1
	s_nop 0
	ds_write2st64_b32 v45, v16, v17 offset0:128 offset1:129
	ds_write2st64_b32 v45, v2, v3 offset0:2 offset1:3
	ds_write2st64_b32 v45, v18, v19 offset0:130 offset1:131
	ds_write2st64_b32 v45, v4, v5 offset0:4 offset1:5
	ds_write2st64_b32 v45, v20, v21 offset0:132 offset1:133
	ds_write2st64_b32 v45, v6, v7 offset0:6 offset1:7
	ds_write2st64_b32 v45, v22, v23 offset0:134 offset1:135
	ds_write2st64_b32 v45, v8, v9 offset0:8 offset1:9
	ds_write2st64_b32 v45, v24, v25 offset0:136 offset1:137
	ds_write2st64_b32 v45, v10, v11 offset0:10 offset1:11
	ds_write2st64_b32 v45, v26, v27 offset0:138 offset1:139
	ds_write2st64_b32 v45, v12, v13 offset0:12 offset1:13
	ds_write2st64_b32 v45, v28, v29 offset0:140 offset1:141
	ds_write2st64_b32 v45, v14, v15 offset0:14 offset1:15
	ds_write2st64_b32 v45, v30, v31 offset0:142 offset1:143
	s_waitcnt lgkmcnt(0)
	s_barrier
	ds_read2st64_b32 v[0:1], v44 offset1:1
	ds_read2st64_b32 v[2:3], v44 offset0:16 offset1:17
	ds_read2st64_b32 v[4:5], v44 offset0:32 offset1:33
	ds_read2st64_b32 v[6:7], v44 offset0:48 offset1:49
	ds_read2st64_b32 v[8:9], v44 offset0:128 offset1:129
	ds_read2st64_b32 v[10:11], v44 offset0:144 offset1:145
	ds_read2st64_b32 v[12:13], v44 offset0:160 offset1:161
	ds_read2st64_b32 v[14:15], v44 offset0:176 offset1:177
	ds_read2st64_b32 v[16:17], v44 offset0:64 offset1:65
	ds_read2st64_b32 v[18:19], v44 offset0:80 offset1:81
	ds_read2st64_b32 v[20:21], v44 offset0:96 offset1:97
	ds_read2st64_b32 v[22:23], v44 offset0:112 offset1:113
	ds_read2st64_b32 v[24:25], v44 offset0:192 offset1:193
	ds_read2st64_b32 v[26:27], v44 offset0:208 offset1:209
	ds_read2st64_b32 v[28:29], v44 offset0:224 offset1:225
	ds_read2st64_b32 v[30:31], v44 offset0:240 offset1:241
	s_waitcnt lgkmcnt(11)
	v_mov_b32_e32 v38, v8
	v_mov_b32_e32 v39, v0
	v_pk_add_f32 v[38:39], v[38:39], 0 op_sel_hi:[1,0]
	s_waitcnt lgkmcnt(10)
	v_mov_b32_e32 v40, v10
	v_mov_b32_e32 v41, v2
	v_mov_b32_e32 v0, v9
	v_pk_add_f32 v[38:39], v[38:39], v[40:41]
	s_waitcnt lgkmcnt(9)
	v_mov_b32_e32 v40, v12
	v_mov_b32_e32 v41, v4
	v_pk_add_f32 v[0:1], v[0:1], 0 op_sel_hi:[1,0]
	v_mov_b32_e32 v2, v11
	v_pk_add_f32 v[38:39], v[38:39], v[40:41]
	s_waitcnt lgkmcnt(8)
	v_mov_b32_e32 v40, v14
	v_mov_b32_e32 v41, v6
	v_pk_add_f32 v[0:1], v[0:1], v[2:3]
	v_mov_b32_e32 v4, v13
	v_pk_add_f32 v[38:39], v[38:39], v[40:41]
	s_waitcnt lgkmcnt(3)
	v_mov_b32_e32 v40, v24
	v_mov_b32_e32 v41, v16
	v_pk_add_f32 v[0:1], v[0:1], v[4:5]
	v_mov_b32_e32 v6, v15
	v_pk_add_f32 v[38:39], v[38:39], v[40:41]
	s_waitcnt lgkmcnt(2)
	v_mov_b32_e32 v40, v26
	v_mov_b32_e32 v41, v18
	v_pk_add_f32 v[0:1], v[0:1], v[6:7]
	v_mov_b32_e32 v16, v25
	v_pk_add_f32 v[38:39], v[38:39], v[40:41]
	s_waitcnt lgkmcnt(1)
	v_mov_b32_e32 v40, v28
	v_mov_b32_e32 v41, v20
	v_pk_add_f32 v[0:1], v[0:1], v[16:17]
	v_mov_b32_e32 v18, v27
	v_pk_add_f32 v[38:39], v[38:39], v[40:41]
	s_waitcnt lgkmcnt(0)
	v_mov_b32_e32 v40, v30
	v_mov_b32_e32 v41, v22
	v_pk_add_f32 v[0:1], v[0:1], v[18:19]
	v_mov_b32_e32 v20, v29
	v_pk_add_f32 v[38:39], v[38:39], v[40:41]
	v_pk_add_f32 v[0:1], v[0:1], v[20:21]
	v_mov_b32_e32 v22, v31
	v_pk_add_f32 v[0:1], v[0:1], v[22:23]
	v_mul_f32_e32 v2, 0xbfb8aa3b, v39
	v_exp_f32_e32 v2, v2
	v_mul_f32_e32 v3, 0xbfb8aa3b, v1
	v_exp_f32_e32 v3, v3
	s_lshl_b32 s0, s17, 3
	v_add_f32_e32 v2, 1.0, v2
	v_rcp_f32_e32 v4, v2
	v_add_f32_e32 v2, 1.0, v3
	v_rcp_f32_e32 v3, v2
	s_andn2_b32 s0, s0, 31
	v_mul_f32_e32 v4, v39, v4
	v_mul_f32_e32 v4, v38, v4
	v_mul_f32_e32 v1, v1, v3
	v_mul_f32_e32 v0, v0, v1
	v_add_u32_e32 v2, s0, v43
	v_cvt_pk_bf16_f32 v4, v4, v0
	v_mov_b64_e32 v[0:1], s[4:5]
	s_add_i32 s10, s10, 1
	s_add_i32 s11, s11, s70
	s_add_i32 s16, s16, s46
	s_add_i32 s12, s12, s71
	v_mad_u64_u32 v[0:1], s[0:1], v36, s15, v[0:1]
	v_ashrrev_i32_e32 v3, 31, v2
	s_cmp_eq_u32 s10, s44
	v_lshl_add_u64 v[0:1], v[2:3], 1, v[0:1]
	s_cselect_b64 s[8:9], -1, 0
	global_store_dword v[0:1], v4, off
	s_branch .LBB0_198

; template <int MODE>
; __device__ __forceinline__ void small_gemm(LAS unsigned char* lds, const bf16* A, const bf16* Bt, int N, int K, bf16* O, int ldc, int act_cols, const float* bias, const bf16* Yv, int ldy, int it0, int it1) {
;     ...
;     for (int it = it0; it < it1; ++it) {
;         const int item = BX + it * GSZ; if (item >= nitems) break;
;         const int rt = item & 3, ct = item >> 2;
;         const int hc = 32 * ct + tl;
;         const int brow = (MODE == 3) ? (256 * (hc >> 7) + (hc & 127)) : hc;
;         const bf16* ap = A + (size_t)(32 * rt + tl) * K + wave * kw + 8 * hh;
;         const bf16* bp = Bt + (size_t)brow * K + wave * kw + 8 * hh;
;         v16f acc0, acc1;
; #pragma unroll
;         for (int r = 0; r < 16; ++r) { acc0[r] = 0.f; acc1[r] = 0.f; }
; #pragma unroll 4
;         for (int ks = 0; ks < nks; ++ks) {
;             const bfx8 a = *(const bfx8*)(ap + 16 * ks);
;             const bfx8 b0 = *(const bfx8*)(bp + 16 * ks);
;             acc0 = __builtin_amdgcn_mfma_f32_32x32x16_bf16(b0, a, acc0, 0, 0, 0);
;             if (MODE == 3) { const bfx8 b1 = *(const bfx8*)(bp + (size_t)128 * K + 16 * ks); acc1 = __builtin_amdgcn_mfma_f32_32x32x16_bf16(b1, a, acc1, 0, 0, 0); }
;         }
.LBB0_223:
	v_and_b32_e32 v70, 63, v182
	v_lshrrev_b32_e32 v71, 6, v182
	s_nop 0
	v_readfirstlane_b32 s98, v71
	s_mul_i32 m0, s98, 0x2400
	s_add_i32 m0, m0, 0x10000
	v_lshrrev_b32_e32 v71, 3, v70
	v_and_b32_e32 v74, 7, v70
	v_lshlrev_b32_e32 v74, 4, v74
	v_mul_u32_u24_e32 v72, 0x90, v71
	v_add3_u32 v72, v72, v74, m0
	v_mul_u32_u24_e32 v73, 0x90, v42
	v_lshrrev_b32_e32 v76, 5, v70
	v_lshl_add_u32 v73, v76, 4, v73
	v_add_u32_e32 v73, m0, v73
	v_lshlrev_b32_e32 v76, 4, v76
	v_sub_u32_e32 v76, v74, v76
	v_sub_u32_e32 v71, v71, v42
	v_lshl_add_u32 v76, v71, 11, v76
	v_ashrrev_i32_e32 v77, 31, v76
	v_lshl_add_u64 v[78:79], v[38:39], 0, v[76:77]
	v_add_co_u32_e32 v54, vcc, s10, v78
	s_nop 1
	v_addc_co_u32_e32 v55, vcc, 0, v79, vcc
	v_add_co_u32_e32 v62, vcc, s11, v78
	s_nop 1
	v_addc_co_u32_e32 v63, vcc, 0, v79, vcc
	v_subrev_u32_e32 v76, 64, v76
	v_ashrrev_i32_e32 v77, 31, v76
	v_lshl_add_u64 v[46:47], v[40:41], 0, v[76:77]
	s_mov_b32 s100, 0x4000
	s_mov_b32 s101, 0
	v_lshl_add_u64 v[48:49], v[46:47], 0, s[100:101]
	v_lshl_add_u64 v[50:51], v[48:49], 0, s[100:101]
	v_lshl_add_u64 v[52:53], v[50:51], 0, s[100:101]
	v_lshl_add_u64 v[56:57], v[54:55], 0, s[100:101]
	v_lshl_add_u64 v[58:59], v[56:57], 0, s[100:101]
	v_lshl_add_u64 v[60:61], v[58:59], 0, s[100:101]
	v_lshl_add_u64 v[64:65], v[62:63], 0, s[100:101]
	v_lshl_add_u64 v[66:67], v[64:65], 0, s[100:101]
	v_lshl_add_u64 v[68:69], v[66:67], 0, s[100:101]
	global_load_dwordx4 v[80:83], v[46:47], off
	global_load_dwordx4 v[84:87], v[48:49], off
	global_load_dwordx4 v[88:91], v[50:51], off
	global_load_dwordx4 v[92:95], v[52:53], off
	global_load_dwordx4 v[96:99], v[54:55], off
	global_load_dwordx4 v[100:103], v[56:57], off
	global_load_dwordx4 v[104:107], v[58:59], off
	global_load_dwordx4 v[108:111], v[60:61], off
	global_load_dwordx4 v[112:115], v[62:63], off
	global_load_dwordx4 v[116:119], v[64:65], off
	global_load_dwordx4 v[120:123], v[66:67], off
	global_load_dwordx4 v[124:127], v[68:69], off
	global_load_dwordx4 v[128:131], v[46:47], off offset:128
	global_load_dwordx4 v[132:135], v[48:49], off offset:128
	global_load_dwordx4 v[136:139], v[50:51], off offset:128
	global_load_dwordx4 v[140:143], v[52:53], off offset:128
	global_load_dwordx4 v[144:147], v[54:55], off offset:128
	global_load_dwordx4 v[148:151], v[56:57], off offset:128
	global_load_dwordx4 v[152:155], v[58:59], off offset:128
	global_load_dwordx4 v[156:159], v[60:61], off offset:128
	global_load_dwordx4 v[160:163], v[62:63], off offset:128
	global_load_dwordx4 v[164:167], v[64:65], off offset:128
	global_load_dwordx4 v[168:171], v[66:67], off offset:128
	global_load_dwordx4 v[172:175], v[68:69], off offset:128
	s_waitcnt vmcnt(12)
	ds_write_b128 v72, v[80:83]
	ds_write_b128 v72, v[84:87] offset:1152
	ds_write_b128 v72, v[88:91] offset:2304
	ds_write_b128 v72, v[92:95] offset:3456
	ds_write_b128 v72, v[96:99] offset:4608
	ds_write_b128 v72, v[100:103] offset:5760
	ds_write_b128 v72, v[104:107] offset:6912
	ds_write_b128 v72, v[108:111] offset:8064
	s_waitcnt lgkmcnt(0)
	ds_read_b128 v[192:195], v73
	ds_read_b128 v[208:211], v73 offset:4608
	ds_read_b128 v[196:199], v73 offset:32
	ds_read_b128 v[212:215], v73 offset:4640
	ds_read_b128 v[200:203], v73 offset:64
	ds_read_b128 v[216:219], v73 offset:4672
	ds_read_b128 v[204:207], v73 offset:96
	ds_read_b128 v[220:223], v73 offset:4704
	s_waitcnt lgkmcnt(6)
	v_mfma_f32_32x32x16_bf16 v[0:15], v[208:211], v[192:195], v[0:15]
	s_waitcnt lgkmcnt(4)
	v_mfma_f32_32x32x16_bf16 v[0:15], v[212:215], v[196:199], v[0:15]
	s_waitcnt lgkmcnt(2)
	v_mfma_f32_32x32x16_bf16 v[0:15], v[216:219], v[200:203], v[0:15]
	s_waitcnt lgkmcnt(0)
	v_mfma_f32_32x32x16_bf16 v[0:15], v[220:223], v[204:207], v[0:15]
	ds_write_b128 v72, v[112:115] offset:4608
	ds_write_b128 v72, v[116:119] offset:5760
	ds_write_b128 v72, v[120:123] offset:6912
	ds_write_b128 v72, v[124:127] offset:8064
	s_waitcnt lgkmcnt(0)
	ds_read_b128 v[208:211], v73 offset:4608
	ds_read_b128 v[212:215], v73 offset:4640
	ds_read_b128 v[216:219], v73 offset:4672
	ds_read_b128 v[220:223], v73 offset:4704
	s_waitcnt lgkmcnt(3)
	v_mfma_f32_32x32x16_bf16 v[16:31], v[208:211], v[192:195], v[16:31]
	s_waitcnt lgkmcnt(2)
	v_mfma_f32_32x32x16_bf16 v[16:31], v[212:215], v[196:199], v[16:31]
	s_waitcnt lgkmcnt(1)
	v_mfma_f32_32x32x16_bf16 v[16:31], v[216:219], v[200:203], v[16:31]
	s_waitcnt lgkmcnt(0)
	v_mfma_f32_32x32x16_bf16 v[16:31], v[220:223], v[204:207], v[16:31]
	s_waitcnt vmcnt(0)
	s_waitcnt lgkmcnt(0)
	ds_write_b128 v72, v[128:131]
	ds_write_b128 v72, v[132:135] offset:1152
	ds_write_b128 v72, v[136:139] offset:2304
	ds_write_b128 v72, v[140:143] offset:3456
	ds_write_b128 v72, v[144:147] offset:4608
	ds_write_b128 v72, v[148:151] offset:5760
	ds_write_b128 v72, v[152:155] offset:6912
	ds_write_b128 v72, v[156:159] offset:8064
	s_waitcnt lgkmcnt(0)
	ds_read_b128 v[192:195], v73
	ds_read_b128 v[208:211], v73 offset:4608
	ds_read_b128 v[196:199], v73 offset:32
	ds_read_b128 v[212:215], v73 offset:4640
	ds_read_b128 v[200:203], v73 offset:64
	ds_read_b128 v[216:219], v73 offset:4672
	ds_read_b128 v[204:207], v73 offset:96
	ds_read_b128 v[220:223], v73 offset:4704
	s_waitcnt lgkmcnt(6)
	v_mfma_f32_32x32x16_bf16 v[0:15], v[208:211], v[192:195], v[0:15]
	s_waitcnt lgkmcnt(4)
	v_mfma_f32_32x32x16_bf16 v[0:15], v[212:215], v[196:199], v[0:15]
	s_waitcnt lgkmcnt(2)
	v_mfma_f32_32x32x16_bf16 v[0:15], v[216:219], v[200:203], v[0:15]
	s_waitcnt lgkmcnt(0)
	v_mfma_f32_32x32x16_bf16 v[0:15], v[220:223], v[204:207], v[0:15]
	ds_write_b128 v72, v[160:163] offset:4608
	ds_write_b128 v72, v[164:167] offset:5760
	ds_write_b128 v72, v[168:171] offset:6912
	ds_write_b128 v72, v[172:175] offset:8064
	s_waitcnt lgkmcnt(0)
	ds_read_b128 v[208:211], v73 offset:4608
	ds_read_b128 v[212:215], v73 offset:4640
	ds_read_b128 v[216:219], v73 offset:4672
	ds_read_b128 v[220:223], v73 offset:4704
	s_waitcnt lgkmcnt(3)
	v_mfma_f32_32x32x16_bf16 v[16:31], v[208:211], v[192:195], v[16:31]
	s_waitcnt lgkmcnt(2)
	v_mfma_f32_32x32x16_bf16 v[16:31], v[212:215], v[196:199], v[16:31]
	s_waitcnt lgkmcnt(1)
	v_mfma_f32_32x32x16_bf16 v[16:31], v[216:219], v[200:203], v[16:31]
	s_waitcnt lgkmcnt(0)
	v_mfma_f32_32x32x16_bf16 v[16:31], v[220:223], v[204:207], v[16:31]
	s_movk_i32 s8, 0x100
	s_barrier
; __device__ __forceinline__ unsigned cvt_pk_bf16(float lo, float hi) { unsigned r; asm volatile("v_cvt_pk_bf16_f32 %0, %1, %2" : "=v"(r) : "v"(lo), "v"(hi)); return r; }
; __device__ __forceinline__ float bf_lo(unsigned w) { return __uint_as_float(w << 16); }
; __device__ __forceinline__ float bf_hi(unsigned w) { return __uint_as_float(w & 0xffff0000u); }
; __device__ __forceinline__ float gelu_t(float x) { const float u = 1.5957691216057308f * (x + 0.044715f * x * x * x); return x * sigmoid_f(u); }
; __device__ __forceinline__ float sigmoid_f(float x) { return __builtin_amdgcn_rcpf(1.0f + __expf(-x)); }
; __device__ __forceinline__ float silu_f(float x) { return x * sigmoid_f(x); }
; template <int MODE>
; __device__ __forceinline__ void small_gemm(LAS unsigned char* lds, const bf16* A, const bf16* Bt, int N, int K, bf16* O, int ldc, int act_cols, const float* bias, const bf16* Yv, int ldy, int it0, int it1) {
;     ...
;         __syncthreads();
; #pragma unroll
;         for (int r = 0; r < 16; ++r) { red[(wave * 16 + r) * 64 + lane] = acc0[r]; if (MODE == 3) red[8192 + (wave * 16 + r) * 64 + lane] = acc1[r]; }
;         __syncthreads();
;         float v0[2], v1[2];
; #pragma unroll
;         for (int e = 0; e < 2; ++e) { float s0 = 0.f, s1 = 0.f;
; #pragma unroll
;             for (int w = 0; w < 8; ++w) { s0 += red[(w * 16 + 2 * wave + e) * 64 + lane]; if (MODE == 3) s1 += red[8192 + (w * 16 + 2 * wave + e) * 64 + lane]; }
;             v0[e] = s0; v1[e] = s1; }
;         const int reg = 2 * wave;
;         const int col = 32 * ct + (reg & 3) + 8 * (reg >> 2) + 4 * hh;
;         const size_t row = (size_t)(32 * rt + tl);
;         float o0 = v0[0], o1 = v0[1];
;         if (MODE == 1) { if (col < act_cols) { o0 = gelu_t(o0); o1 = gelu_t(o1); } }
;         if (MODE == 2) { const unsigned y = *(const unsigned*)(Yv + row * ldy + col); o0 = bf_lo(y) * pg8::sigmoid_f(o0 + bias[col]); o1 = bf_hi(y) * pg8::sigmoid_f(o1 + bias[col + 1]); }
;         if (MODE == 3) { o0 = pg8::silu_f(o0) * v1[0]; o1 = pg8::silu_f(o1) * v1[1]; }
;         *(unsigned*)(O + row * ldc + col) = cvt_pk_bf16(o0, o1);
	s_nop 7
	ds_write2st64_b32 v45, v0, v1 offset1:1
	s_nop 0
	ds_write2st64_b32 v45, v16, v17 offset0:128 offset1:129
	ds_write2st64_b32 v45, v2, v3 offset0:2 offset1:3
	ds_write2st64_b32 v45, v18, v19 offset0:130 offset1:131
	ds_write2st64_b32 v45, v4, v5 offset0:4 offset1:5
	ds_write2st64_b32 v45, v20, v21 offset0:132 offset1:133
	ds_write2st64_b32 v45, v6, v7 offset0:6 offset1:7
	ds_write2st64_b32 v45, v22, v23 offset0:134 offset1:135
	ds_write2st64_b32 v45, v8, v9 offset0:8 offset1:9
	ds_write2st64_b32 v45, v24, v25 offset0:136 offset1:137
	ds_write2st64_b32 v45, v10, v11 offset0:10 offset1:11
	ds_write2st64_b32 v45, v26, v27 offset0:138 offset1:139
	ds_write2st64_b32 v45, v12, v13 offset0:12 offset1:13
	ds_write2st64_b32 v45, v28, v29 offset0:140 offset1:141
	ds_write2st64_b32 v45, v14, v15 offset0:14 offset1:15
	ds_write2st64_b32 v45, v30, v31 offset0:142 offset1:143
	s_waitcnt lgkmcnt(0)
	s_barrier
	ds_read2st64_b32 v[0:1], v44 offset1:1
	ds_read2st64_b32 v[2:3], v44 offset0:16 offset1:17
	ds_read2st64_b32 v[4:5], v44 offset0:32 offset1:33
	ds_read2st64_b32 v[6:7], v44 offset0:48 offset1:49
	ds_read2st64_b32 v[8:9], v44 offset0:128 offset1:129
	ds_read2st64_b32 v[10:11], v44 offset0:144 offset1:145
	ds_read2st64_b32 v[12:13], v44 offset0:160 offset1:161
	ds_read2st64_b32 v[14:15], v44 offset0:176 offset1:177
	ds_read2st64_b32 v[16:17], v44 offset0:64 offset1:65
	ds_read2st64_b32 v[18:19], v44 offset0:80 offset1:81
	ds_read2st64_b32 v[20:21], v44 offset0:96 offset1:97
	ds_read2st64_b32 v[22:23], v44 offset0:112 offset1:113
	ds_read2st64_b32 v[24:25], v44 offset0:192 offset1:193
	ds_read2st64_b32 v[26:27], v44 offset0:208 offset1:209
	ds_read2st64_b32 v[28:29], v44 offset0:224 offset1:225
	ds_read2st64_b32 v[30:31], v44 offset0:240 offset1:241
	s_waitcnt lgkmcnt(11)
	v_mov_b32_e32 v38, v8
	v_mov_b32_e32 v39, v0
	v_pk_add_f32 v[38:39], v[38:39], 0 op_sel_hi:[1,0]
	s_waitcnt lgkmcnt(10)
	v_mov_b32_e32 v40, v10
	v_mov_b32_e32 v41, v2
	v_mov_b32_e32 v0, v9
	v_pk_add_f32 v[38:39], v[38:39], v[40:41]
	s_waitcnt lgkmcnt(9)
	v_mov_b32_e32 v40, v12
	v_mov_b32_e32 v41, v4
	v_pk_add_f32 v[0:1], v[0:1], 0 op_sel_hi:[1,0]
	v_mov_b32_e32 v2, v11
	v_pk_add_f32 v[38:39], v[38:39], v[40:41]
	s_waitcnt lgkmcnt(8)
	v_mov_b32_e32 v40, v14
	v_mov_b32_e32 v41, v6
	v_pk_add_f32 v[0:1], v[0:1], v[2:3]
	v_mov_b32_e32 v4, v13
	v_pk_add_f32 v[38:39], v[38:39], v[40:41]
	s_waitcnt lgkmcnt(3)
	v_mov_b32_e32 v40, v24
	v_mov_b32_e32 v41, v16
	v_pk_add_f32 v[0:1], v[0:1], v[4:5]
	v_mov_b32_e32 v6, v15
	v_pk_add_f32 v[38:39], v[38:39], v[40:41]
	s_waitcnt lgkmcnt(2)
	v_mov_b32_e32 v40, v26
	v_mov_b32_e32 v41, v18
	v_pk_add_f32 v[0:1], v[0:1], v[6:7]
	v_mov_b32_e32 v16, v25
	v_pk_add_f32 v[38:39], v[38:39], v[40:41]
	s_waitcnt lgkmcnt(1)
	v_mov_b32_e32 v40, v28
	v_mov_b32_e32 v41, v20
	v_pk_add_f32 v[0:1], v[0:1], v[16:17]
	v_mov_b32_e32 v18, v27
	v_pk_add_f32 v[38:39], v[38:39], v[40:41]
	s_waitcnt lgkmcnt(0)
	v_mov_b32_e32 v40, v30
	v_mov_b32_e32 v41, v22
	v_pk_add_f32 v[0:1], v[0:1], v[18:19]
	v_mov_b32_e32 v20, v29
	v_pk_add_f32 v[38:39], v[38:39], v[40:41]
	v_pk_add_f32 v[0:1], v[0:1], v[20:21]
	v_mov_b32_e32 v22, v31
	v_pk_add_f32 v[0:1], v[0:1], v[22:23]
	v_mul_f32_e32 v2, 0xbfb8aa3b, v39
	v_exp_f32_e32 v2, v2
	v_mul_f32_e32 v3, 0xbfb8aa3b, v1
	v_exp_f32_e32 v3, v3
	s_lshl_b32 s0, s17, 3
	v_add_f32_e32 v2, 1.0, v2
	v_rcp_f32_e32 v4, v2
	v_add_f32_e32 v2, 1.0, v3
	v_rcp_f32_e32 v3, v2
	s_andn2_b32 s0, s0, 31
	v_mul_f32_e32 v4, v39, v4
	v_mul_f32_e32 v4, v38, v4
	v_mul_f32_e32 v1, v1, v3
	v_mul_f32_e32 v0, v0, v1
	v_cvt_pk_bf16_f32 v4, v4, v0
	v_mov_b64_e32 v[0:1], s[4:5]
	v_add_u32_e32 v2, s0, v43
	v_mad_u64_u32 v[0:1], s[0:1], v36, s12, v[0:1]
	s_add_i32 s0, s16, 1
	s_add_i32 s15, s15, s70
	s_add_i32 s14, s14, s46
	s_add_i32 s13, s13, s71
	v_ashrrev_i32_e32 v3, 31, v2
	s_cmp_gt_u32 s16, 2
	v_lshl_add_u64 v[0:1], v[2:3], 1, v[0:1]
	s_cselect_b64 s[8:9], -1, 0
	s_mov_b32 s16, s0
	global_store_dword v[0:1], v4, off
	s_branch .LBB0_220

; __device__ __forceinline__ float gelu_t(float x) { const float u = 1.5957691216057308f * (x + 0.044715f * x * x * x); return x * sigmoid_f(u); }
; template <int MODE>
; __device__ __forceinline__ void small_gemm(LAS unsigned char* lds, const bf16* A, const bf16* Bt, int N, int K, bf16* O, int ldc, int act_cols, const float* bias, const bf16* Yv, int ldy, int it0, int it1) {
;     ...
;     for (int it = it0; it < it1; ++it) {
;         const int item = BX + it * GSZ; if (item >= nitems) break;
;         const int rt = item & 3, ct = item >> 2;
;         const int hc = 32 * ct + tl;
;         const int brow = (MODE == 3) ? (256 * (hc >> 7) + (hc & 127)) : hc;
;         const bf16* ap = A + (size_t)(32 * rt + tl) * K + wave * kw + 8 * hh;
;         const bf16* bp = Bt + (size_t)brow * K + wave * kw + 8 * hh;
;         v16f acc0, acc1;
; #pragma unroll
;         for (int r = 0; r < 16; ++r) { acc0[r] = 0.f; acc1[r] = 0.f; }
; #pragma unroll 4
;         for (int ks = 0; ks < nks; ++ks) {
;             const bfx8 a = *(const bfx8*)(ap + 16 * ks);
;             const bfx8 b0 = *(const bfx8*)(bp + 16 * ks);
;             acc0 = __builtin_amdgcn_mfma_f32_32x32x16_bf16(b0, a, acc0, 0, 0, 0);
;             if (MODE == 3) { const bfx8 b1 = *(const bfx8*)(bp + (size_t)128 * K + 16 * ks); acc1 = __builtin_amdgcn_mfma_f32_32x32x16_bf16(b1, a, acc1, 0, 0, 0); }
;         }
;         __syncthreads();
; #pragma unroll
;         for (int r = 0; r < 16; ++r) { red[(wave * 16 + r) * 64 + lane] = acc0[r]; if (MODE == 3) red[8192 + (wave * 16 + r) * 64 + lane] = acc1[r]; }
;         __syncthreads();
;         float v0[2], v1[2];
; #pragma unroll
;         for (int e = 0; e < 2; ++e) { float s0 = 0.f, s1 = 0.f;
; #pragma unroll
;             for (int w = 0; w < 8; ++w) { s0 += red[(w * 16 + 2 * wave + e) * 64 + lane]; if (MODE == 3) s1 += red[8192 + (w * 16 + 2 * wave + e) * 64 + lane]; }
;             v0[e] = s0; v1[e] = s1; }
;         const int reg = 2 * wave;
;         const int col = 32 * ct + (reg & 3) + 8 * (reg >> 2) + 4 * hh;
;         const size_t row = (size_t)(32 * rt + tl);
;         float o0 = v0[0], o1 = v0[1];
;         if (MODE == 1) { if (col < act_cols) { o0 = gelu_t(o0); o1 = gelu_t(o1); } }
.LBB0_480:
	v_and_b32_e32 v172, 63, v182
	v_lshrrev_b32_e32 v173, 6, v182
	s_nop 0
	v_readfirstlane_b32 s98, v173
	s_mul_i32 m0, s98, 0x2400
	s_add_i32 m0, m0, 0x10000
	v_lshrrev_b32_e32 v173, 3, v172
	v_and_b32_e32 v176, 7, v172
	v_lshlrev_b32_e32 v176, 4, v176
	v_mul_u32_u24_e32 v174, 0x90, v173
	v_add3_u32 v174, v174, v176, m0
	v_mul_u32_u24_e32 v175, 0x90, v26
	v_lshrrev_b32_e32 v178, 5, v172
	v_lshl_add_u32 v175, v178, 4, v175
	v_add_u32_e32 v175, m0, v175
	v_lshlrev_b32_e32 v178, 4, v178
	v_sub_u32_e32 v178, v176, v178
	v_sub_u32_e32 v173, v173, v26
	v_lshl_add_u32 v178, v173, 11, v178
	v_subrev_u32_e32 v178, 64, v178
	v_ashrrev_i32_e32 v179, 31, v178
	v_lshl_add_u64 v[142:143], v[22:23], 0, v[178:179]
	v_lshl_add_u64 v[150:151], v[24:25], 0, v[178:179]
	s_mov_b32 s100, 0x4000
	s_mov_b32 s101, 0
	v_lshl_add_u64 v[144:145], v[142:143], 0, s[100:101]
	v_lshl_add_u64 v[146:147], v[144:145], 0, s[100:101]
	v_lshl_add_u64 v[148:149], v[146:147], 0, s[100:101]
	v_lshl_add_u64 v[152:153], v[150:151], 0, s[100:101]
	v_lshl_add_u64 v[154:155], v[152:153], 0, s[100:101]
	v_lshl_add_u64 v[156:157], v[154:155], 0, s[100:101]
	global_load_dwordx4 v[30:33], v[142:143], off
	global_load_dwordx4 v[34:37], v[144:145], off
	global_load_dwordx4 v[38:41], v[146:147], off
	global_load_dwordx4 v[42:45], v[148:149], off
	global_load_dwordx4 v[46:49], v[150:151], off
	global_load_dwordx4 v[50:53], v[152:153], off
	global_load_dwordx4 v[54:57], v[154:155], off
	global_load_dwordx4 v[58:61], v[156:157], off
	global_load_dwordx4 v[62:65], v[142:143], off offset:128
	global_load_dwordx4 v[66:69], v[144:145], off offset:128
	global_load_dwordx4 v[70:73], v[146:147], off offset:128
	global_load_dwordx4 v[74:77], v[148:149], off offset:128
	global_load_dwordx4 v[78:81], v[150:151], off offset:128
	global_load_dwordx4 v[82:85], v[152:153], off offset:128
	global_load_dwordx4 v[86:89], v[154:155], off offset:128
	global_load_dwordx4 v[90:93], v[156:157], off offset:128
	s_waitcnt vmcnt(8)
	ds_write_b128 v174, v[30:33]
	ds_write_b128 v174, v[34:37] offset:1152
	ds_write_b128 v174, v[38:41] offset:2304
	ds_write_b128 v174, v[42:45] offset:3456
	ds_write_b128 v174, v[46:49] offset:4608
	ds_write_b128 v174, v[50:53] offset:5760
	ds_write_b128 v174, v[54:57] offset:6912
	ds_write_b128 v174, v[58:61] offset:8064
	s_waitcnt lgkmcnt(0)
	ds_read_b128 v[110:113], v175
	ds_read_b128 v[126:129], v175 offset:4608
	ds_read_b128 v[114:117], v175 offset:32
	ds_read_b128 v[130:133], v175 offset:4640
	ds_read_b128 v[118:121], v175 offset:64
	ds_read_b128 v[134:137], v175 offset:4672
	ds_read_b128 v[122:125], v175 offset:96
	ds_read_b128 v[138:141], v175 offset:4704
	s_waitcnt lgkmcnt(6)
	v_mfma_f32_32x32x16_bf16 v[0:15], v[110:113], v[126:129], v[0:15]
	s_waitcnt lgkmcnt(4)
	v_mfma_f32_32x32x16_bf16 v[0:15], v[114:117], v[130:133], v[0:15]
	s_waitcnt lgkmcnt(2)
	v_mfma_f32_32x32x16_bf16 v[0:15], v[118:121], v[134:137], v[0:15]
	s_waitcnt lgkmcnt(0)
	v_mfma_f32_32x32x16_bf16 v[0:15], v[122:125], v[138:141], v[0:15]
	s_waitcnt vmcnt(0)
	ds_write_b128 v174, v[62:65]
	ds_write_b128 v174, v[66:69] offset:1152
	ds_write_b128 v174, v[70:73] offset:2304
	ds_write_b128 v174, v[74:77] offset:3456
	ds_write_b128 v174, v[78:81] offset:4608
	ds_write_b128 v174, v[82:85] offset:5760
	ds_write_b128 v174, v[86:89] offset:6912
	ds_write_b128 v174, v[90:93] offset:8064
	s_waitcnt lgkmcnt(0)
	ds_read_b128 v[110:113], v175
	ds_read_b128 v[126:129], v175 offset:4608
	ds_read_b128 v[114:117], v175 offset:32
	ds_read_b128 v[130:133], v175 offset:4640
	ds_read_b128 v[118:121], v175 offset:64
	ds_read_b128 v[134:137], v175 offset:4672
	ds_read_b128 v[122:125], v175 offset:96
	ds_read_b128 v[138:141], v175 offset:4704
	s_waitcnt lgkmcnt(6)
	v_mfma_f32_32x32x16_bf16 v[0:15], v[110:113], v[126:129], v[0:15]
	s_waitcnt lgkmcnt(4)
	v_mfma_f32_32x32x16_bf16 v[0:15], v[114:117], v[130:133], v[0:15]
	s_waitcnt lgkmcnt(2)
	v_mfma_f32_32x32x16_bf16 v[0:15], v[118:121], v[134:137], v[0:15]
	s_waitcnt lgkmcnt(0)
	v_mfma_f32_32x32x16_bf16 v[0:15], v[122:125], v[138:141], v[0:15]
	s_movk_i32 s10, 0x100
	v_add_u32_e32 v22, s13, v27
	s_barrier
	s_nop 8
	ds_write2st64_b32 v22, v0, v1 offset1:1
	ds_write2st64_b32 v22, v2, v3 offset0:2 offset1:3
	ds_write2st64_b32 v22, v4, v5 offset0:4 offset1:5
	ds_write2st64_b32 v22, v6, v7 offset0:6 offset1:7
	ds_write2st64_b32 v22, v8, v9 offset0:8 offset1:9
	ds_write2st64_b32 v22, v10, v11 offset0:10 offset1:11
	ds_write2st64_b32 v22, v12, v13 offset0:12 offset1:13
	ds_write2st64_b32 v22, v14, v15 offset0:14 offset1:15
	v_add_u32_e32 v14, s14, v27
	s_waitcnt lgkmcnt(0)
	s_barrier
	ds_read2st64_b32 v[0:1], v14 offset1:1
	ds_read2st64_b32 v[2:3], v14 offset0:16 offset1:17
	ds_read2st64_b32 v[4:5], v14 offset0:32 offset1:33
	ds_read2st64_b32 v[6:7], v14 offset0:48 offset1:49
	ds_read2st64_b32 v[8:9], v14 offset0:64 offset1:65
	ds_read2st64_b32 v[10:11], v14 offset0:80 offset1:81
	ds_read2st64_b32 v[12:13], v14 offset0:96 offset1:97
	ds_read2st64_b32 v[14:15], v14 offset0:112 offset1:113
	s_waitcnt lgkmcnt(7)
	v_pk_add_f32 v[0:1], v[0:1], 0 op_sel_hi:[1,0]
	s_lshl_b32 s0, s19, 3
	s_waitcnt lgkmcnt(6)
	v_pk_add_f32 v[0:1], v[0:1], v[2:3]
	s_andn2_b32 s0, s0, 31
	s_waitcnt lgkmcnt(5)
	v_pk_add_f32 v[0:1], v[0:1], v[4:5]
	s_waitcnt lgkmcnt(4)
	v_pk_add_f32 v[0:1], v[0:1], v[6:7]
	s_waitcnt lgkmcnt(3)
	v_pk_add_f32 v[0:1], v[0:1], v[8:9]
	s_waitcnt lgkmcnt(2)
	v_pk_add_f32 v[0:1], v[0:1], v[10:11]
	s_waitcnt lgkmcnt(1)
	v_pk_add_f32 v[0:1], v[0:1], v[12:13]
	s_waitcnt lgkmcnt(0)
	v_pk_add_f32 v[2:3], v[0:1], v[14:15]
	v_add_u32_e32 v0, s0, v28
	v_cmp_gt_i32_e32 vcc, s16, v0
	s_and_saveexec_b64 s[10:11], vcc
	s_cbranch_execz .LBB0_476
	v_mul_f32_e32 v1, 0x3d372713, v2
	v_mul_f32_e32 v1, v2, v1
	v_mul_f32_e32 v4, 0x3d372713, v3
	v_fma_f32 v1, v2, v1, v2
	v_mul_f32_e32 v4, v3, v4
	v_mul_f32_e32 v1, 0x3fcc422a, v1
	v_fma_f32 v4, v3, v4, v3
	v_mul_f32_e32 v1, 0xbfb8aa3b, v1
	v_mul_f32_e32 v4, 0x3fcc422a, v4
	v_exp_f32_e32 v1, v1
	v_mul_f32_e32 v4, 0xbfb8aa3b, v4
	v_exp_f32_e32 v5, v4
	v_add_f32_e32 v1, 1.0, v1
	v_rcp_f32_e32 v4, v1
	v_add_f32_e32 v1, 1.0, v5
	v_rcp_f32_e32 v5, v1
	s_nop 0
	v_pk_mul_f32 v[2:3], v[2:3], v[4:5]
	s_branch .LBB0_476

; __device__ __forceinline__ float gelu_t(float x) { const float u = 1.5957691216057308f * (x + 0.044715f * x * x * x); return x * sigmoid_f(u); }
; template <int MODE>
; __device__ __forceinline__ void small_gemm(LAS unsigned char* lds, const bf16* A, const bf16* Bt, int N, int K, bf16* O, int ldc, int act_cols, const float* bias, const bf16* Yv, int ldy, int it0, int it1) {
;     ...
;     for (int it = it0; it < it1; ++it) {
;         const int item = BX + it * GSZ; if (item >= nitems) break;
;         const int rt = item & 3, ct = item >> 2;
;         const int hc = 32 * ct + tl;
;         const int brow = (MODE == 3) ? (256 * (hc >> 7) + (hc & 127)) : hc;
;         const bf16* ap = A + (size_t)(32 * rt + tl) * K + wave * kw + 8 * hh;
;         const bf16* bp = Bt + (size_t)brow * K + wave * kw + 8 * hh;
;         v16f acc0, acc1;
; #pragma unroll
;         for (int r = 0; r < 16; ++r) { acc0[r] = 0.f; acc1[r] = 0.f; }
; #pragma unroll 4
;         for (int ks = 0; ks < nks; ++ks) {
;             const bfx8 a = *(const bfx8*)(ap + 16 * ks);
;             const bfx8 b0 = *(const bfx8*)(bp + 16 * ks);
;             acc0 = __builtin_amdgcn_mfma_f32_32x32x16_bf16(b0, a, acc0, 0, 0, 0);
;             if (MODE == 3) { const bfx8 b1 = *(const bfx8*)(bp + (size_t)128 * K + 16 * ks); acc1 = __builtin_amdgcn_mfma_f32_32x32x16_bf16(b1, a, acc1, 0, 0, 0); }
;         }
;         __syncthreads();
; #pragma unroll
;         for (int r = 0; r < 16; ++r) { red[(wave * 16 + r) * 64 + lane] = acc0[r]; if (MODE == 3) red[8192 + (wave * 16 + r) * 64 + lane] = acc1[r]; }
;         __syncthreads();
;         float v0[2], v1[2];
; #pragma unroll
;         for (int e = 0; e < 2; ++e) { float s0 = 0.f, s1 = 0.f;
; #pragma unroll
;             for (int w = 0; w < 8; ++w) { s0 += red[(w * 16 + 2 * wave + e) * 64 + lane]; if (MODE == 3) s1 += red[8192 + (w * 16 + 2 * wave + e) * 64 + lane]; }
;             v0[e] = s0; v1[e] = s1; }
;         const int reg = 2 * wave;
;         const int col = 32 * ct + (reg & 3) + 8 * (reg >> 2) + 4 * hh;
;         const size_t row = (size_t)(32 * rt + tl);
;         float o0 = v0[0], o1 = v0[1];
;         if (MODE == 1) { if (col < act_cols) { o0 = gelu_t(o0); o1 = gelu_t(o1); } }
.LBB0_538:
	v_and_b32_e32 v172, 63, v182
	v_lshrrev_b32_e32 v173, 6, v182
	s_nop 0
	v_readfirstlane_b32 s98, v173
	s_mul_i32 m0, s98, 0x2400
	s_add_i32 m0, m0, 0x10000
	v_lshrrev_b32_e32 v173, 3, v172
	v_and_b32_e32 v176, 7, v172
	v_lshlrev_b32_e32 v176, 4, v176
	v_mul_u32_u24_e32 v174, 0x90, v173
	v_add3_u32 v174, v174, v176, m0
	v_mul_u32_u24_e32 v175, 0x90, v26
	v_lshrrev_b32_e32 v178, 5, v172
	v_lshl_add_u32 v175, v178, 4, v175
	v_add_u32_e32 v175, m0, v175
	v_lshlrev_b32_e32 v178, 4, v178
	v_sub_u32_e32 v178, v176, v178
	v_sub_u32_e32 v173, v173, v26
	v_lshl_add_u32 v178, v173, 11, v178
	v_subrev_u32_e32 v178, 64, v178
	v_ashrrev_i32_e32 v179, 31, v178
	v_lshl_add_u64 v[142:143], v[22:23], 0, v[178:179]
	v_lshl_add_u64 v[150:151], v[24:25], 0, v[178:179]
	s_mov_b32 s100, 0x4000
	s_mov_b32 s101, 0
	v_lshl_add_u64 v[144:145], v[142:143], 0, s[100:101]
	v_lshl_add_u64 v[146:147], v[144:145], 0, s[100:101]
	v_lshl_add_u64 v[148:149], v[146:147], 0, s[100:101]
	v_lshl_add_u64 v[152:153], v[150:151], 0, s[100:101]
	v_lshl_add_u64 v[154:155], v[152:153], 0, s[100:101]
	v_lshl_add_u64 v[156:157], v[154:155], 0, s[100:101]
	global_load_dwordx4 v[30:33], v[142:143], off
	global_load_dwordx4 v[34:37], v[144:145], off
	global_load_dwordx4 v[38:41], v[146:147], off
	global_load_dwordx4 v[42:45], v[148:149], off
	global_load_dwordx4 v[46:49], v[150:151], off
	global_load_dwordx4 v[50:53], v[152:153], off
	global_load_dwordx4 v[54:57], v[154:155], off
	global_load_dwordx4 v[58:61], v[156:157], off
	global_load_dwordx4 v[62:65], v[142:143], off offset:128
	global_load_dwordx4 v[66:69], v[144:145], off offset:128
	global_load_dwordx4 v[70:73], v[146:147], off offset:128
	global_load_dwordx4 v[74:77], v[148:149], off offset:128
	global_load_dwordx4 v[78:81], v[150:151], off offset:128
	global_load_dwordx4 v[82:85], v[152:153], off offset:128
	global_load_dwordx4 v[86:89], v[154:155], off offset:128
	global_load_dwordx4 v[90:93], v[156:157], off offset:128
	s_waitcnt vmcnt(8)
	ds_write_b128 v174, v[30:33]
	ds_write_b128 v174, v[34:37] offset:1152
	ds_write_b128 v174, v[38:41] offset:2304
	ds_write_b128 v174, v[42:45] offset:3456
	ds_write_b128 v174, v[46:49] offset:4608
	ds_write_b128 v174, v[50:53] offset:5760
	ds_write_b128 v174, v[54:57] offset:6912
	ds_write_b128 v174, v[58:61] offset:8064
	s_waitcnt lgkmcnt(0)
	ds_read_b128 v[110:113], v175
	ds_read_b128 v[126:129], v175 offset:4608
	ds_read_b128 v[114:117], v175 offset:32
	ds_read_b128 v[130:133], v175 offset:4640
	ds_read_b128 v[118:121], v175 offset:64
	ds_read_b128 v[134:137], v175 offset:4672
	ds_read_b128 v[122:125], v175 offset:96
	ds_read_b128 v[138:141], v175 offset:4704
	s_waitcnt lgkmcnt(6)
	v_mfma_f32_32x32x16_bf16 v[0:15], v[110:113], v[126:129], v[0:15]
	s_waitcnt lgkmcnt(4)
	v_mfma_f32_32x32x16_bf16 v[0:15], v[114:117], v[130:133], v[0:15]
	s_waitcnt lgkmcnt(2)
	v_mfma_f32_32x32x16_bf16 v[0:15], v[118:121], v[134:137], v[0:15]
	s_waitcnt lgkmcnt(0)
	v_mfma_f32_32x32x16_bf16 v[0:15], v[122:125], v[138:141], v[0:15]
	s_waitcnt vmcnt(0)
	ds_write_b128 v174, v[62:65]
	ds_write_b128 v174, v[66:69] offset:1152
	ds_write_b128 v174, v[70:73] offset:2304
	ds_write_b128 v174, v[74:77] offset:3456
	ds_write_b128 v174, v[78:81] offset:4608
	ds_write_b128 v174, v[82:85] offset:5760
	ds_write_b128 v174, v[86:89] offset:6912
	ds_write_b128 v174, v[90:93] offset:8064
	s_waitcnt lgkmcnt(0)
	ds_read_b128 v[110:113], v175
	ds_read_b128 v[126:129], v175 offset:4608
	ds_read_b128 v[114:117], v175 offset:32
	ds_read_b128 v[130:133], v175 offset:4640
	ds_read_b128 v[118:121], v175 offset:64
	ds_read_b128 v[134:137], v175 offset:4672
	ds_read_b128 v[122:125], v175 offset:96
	ds_read_b128 v[138:141], v175 offset:4704
	s_waitcnt lgkmcnt(6)
	v_mfma_f32_32x32x16_bf16 v[0:15], v[110:113], v[126:129], v[0:15]
	s_waitcnt lgkmcnt(4)
	v_mfma_f32_32x32x16_bf16 v[0:15], v[114:117], v[130:133], v[0:15]
	s_waitcnt lgkmcnt(2)
	v_mfma_f32_32x32x16_bf16 v[0:15], v[118:121], v[134:137], v[0:15]
	s_waitcnt lgkmcnt(0)
	v_mfma_f32_32x32x16_bf16 v[0:15], v[122:125], v[138:141], v[0:15]
	s_movk_i32 s10, 0x100
	v_add_u32_e32 v22, s12, v27
	s_barrier
	s_nop 8
	ds_write2st64_b32 v22, v0, v1 offset1:1
	ds_write2st64_b32 v22, v2, v3 offset0:2 offset1:3
	ds_write2st64_b32 v22, v4, v5 offset0:4 offset1:5
	ds_write2st64_b32 v22, v6, v7 offset0:6 offset1:7
	ds_write2st64_b32 v22, v8, v9 offset0:8 offset1:9
	ds_write2st64_b32 v22, v10, v11 offset0:10 offset1:11
	ds_write2st64_b32 v22, v12, v13 offset0:12 offset1:13
	ds_write2st64_b32 v22, v14, v15 offset0:14 offset1:15
	v_add_u32_e32 v14, s13, v27
	s_waitcnt lgkmcnt(0)
	s_barrier
	ds_read2st64_b32 v[0:1], v14 offset1:1
	ds_read2st64_b32 v[2:3], v14 offset0:16 offset1:17
	ds_read2st64_b32 v[4:5], v14 offset0:32 offset1:33
	ds_read2st64_b32 v[6:7], v14 offset0:48 offset1:49
	ds_read2st64_b32 v[8:9], v14 offset0:64 offset1:65
	ds_read2st64_b32 v[10:11], v14 offset0:80 offset1:81
	ds_read2st64_b32 v[12:13], v14 offset0:96 offset1:97
	ds_read2st64_b32 v[14:15], v14 offset0:112 offset1:113
	s_waitcnt lgkmcnt(7)
	v_pk_add_f32 v[0:1], v[0:1], 0 op_sel_hi:[1,0]
	s_lshl_b32 s0, s19, 3
	s_waitcnt lgkmcnt(6)
	v_pk_add_f32 v[0:1], v[0:1], v[2:3]
	s_andn2_b32 s0, s0, 31
	s_waitcnt lgkmcnt(5)
	v_pk_add_f32 v[0:1], v[0:1], v[4:5]
	s_waitcnt lgkmcnt(4)
	v_pk_add_f32 v[0:1], v[0:1], v[6:7]
	s_waitcnt lgkmcnt(3)
	v_pk_add_f32 v[0:1], v[0:1], v[8:9]
	s_waitcnt lgkmcnt(2)
	v_pk_add_f32 v[0:1], v[0:1], v[10:11]
	s_waitcnt lgkmcnt(1)
	v_pk_add_f32 v[0:1], v[0:1], v[12:13]
	s_waitcnt lgkmcnt(0)
	v_pk_add_f32 v[2:3], v[0:1], v[14:15]
	v_add_u32_e32 v0, s0, v28
	v_cmp_gt_i32_e32 vcc, s14, v0
	s_and_saveexec_b64 s[10:11], vcc
	s_cbranch_execz .LBB0_534
	v_mul_f32_e32 v1, 0x3d372713, v2
	v_mul_f32_e32 v1, v2, v1
	v_mul_f32_e32 v4, 0x3d372713, v3
	v_fma_f32 v1, v2, v1, v2
	v_mul_f32_e32 v4, v3, v4
	v_mul_f32_e32 v1, 0x3fcc422a, v1
	v_fma_f32 v4, v3, v4, v3
	v_mul_f32_e32 v1, 0xbfb8aa3b, v1
	v_mul_f32_e32 v4, 0x3fcc422a, v4
	v_exp_f32_e32 v1, v1
	v_mul_f32_e32 v4, 0xbfb8aa3b, v4
	v_exp_f32_e32 v5, v4
	v_add_f32_e32 v1, 1.0, v1
	v_rcp_f32_e32 v4, v1
	v_add_f32_e32 v1, 1.0, v5
	v_rcp_f32_e32 v5, v1
	s_nop 0
	v_pk_mul_f32 v[2:3], v[2:3], v[4:5]
	s_branch .LBB0_534

; template <int MODE>
; __device__ __forceinline__ void small_gemm(LAS unsigned char* lds, const bf16* A, const bf16* Bt, int N, int K, bf16* O, int ldc, int act_cols, const float* bias, const bf16* Yv, int ldy, int it0, int it1) {
;     ...
;     for (int it = it0; it < it1; ++it) {
;         const int item = BX + it * GSZ; if (item >= nitems) break;
;         const int rt = item & 3, ct = item >> 2;
;         const int hc = 32 * ct + tl;
;         const int brow = (MODE == 3) ? (256 * (hc >> 7) + (hc & 127)) : hc;
;         const bf16* ap = A + (size_t)(32 * rt + tl) * K + wave * kw + 8 * hh;
;         const bf16* bp = Bt + (size_t)brow * K + wave * kw + 8 * hh;
;         v16f acc0, acc1;
; #pragma unroll
;         for (int r = 0; r < 16; ++r) { acc0[r] = 0.f; acc1[r] = 0.f; }
; #pragma unroll 4
;         for (int ks = 0; ks < nks; ++ks) {
;             const bfx8 a = *(const bfx8*)(ap + 16 * ks);
;             const bfx8 b0 = *(const bfx8*)(bp + 16 * ks);
;             acc0 = __builtin_amdgcn_mfma_f32_32x32x16_bf16(b0, a, acc0, 0, 0, 0);
;             if (MODE == 3) { const bfx8 b1 = *(const bfx8*)(bp + (size_t)128 * K + 16 * ks); acc1 = __builtin_amdgcn_mfma_f32_32x32x16_bf16(b1, a, acc1, 0, 0, 0); }
;         }
;         __syncthreads();
; #pragma unroll
;         for (int r = 0; r < 16; ++r) { red[(wave * 16 + r) * 64 + lane] = acc0[r]; if (MODE == 3) red[8192 + (wave * 16 + r) * 64 + lane] = acc1[r]; }
;         __syncthreads();
;         float v0[2], v1[2];
; #pragma unroll
;         for (int e = 0; e < 2; ++e) { float s0 = 0.f, s1 = 0.f;
; #pragma unroll
;             for (int w = 0; w < 8; ++w) { s0 += red[(w * 16 + 2 * wave + e) * 64 + lane]; if (MODE == 3) s1 += red[8192 + (w * 16 + 2 * wave + e) * 64 + lane]; }
;             v0[e] = s0; v1[e] = s1; }
;         const int reg = 2 * wave;
;         const int col = 32 * ct + (reg & 3) + 8 * (reg >> 2) + 4 * hh;
;         const size_t row = (size_t)(32 * rt + tl);
;         float o0 = v0[0], o1 = v0[1];
;         if (MODE == 1) { if (col < act_cols) { o0 = gelu_t(o0); o1 = gelu_t(o1); } }
;         if (MODE == 2) { const unsigned y = *(const unsigned*)(Yv + row * ldy + col); o0 = bf_lo(y) * pg8::sigmoid_f(o0 + bias[col]); o1 = bf_hi(y) * pg8::sigmoid_f(o1 + bias[col + 1]); }
;         if (MODE == 3) { o0 = pg8::silu_f(o0) * v1[0]; o1 = pg8::silu_f(o1) * v1[1]; }
.LBB0_910:
	v_and_b32_e32 v172, 63, v182
	v_lshrrev_b32_e32 v173, 6, v182
	s_nop 0
	v_readfirstlane_b32 s98, v173
	s_mul_i32 m0, s98, 0x2400
	s_add_i32 m0, m0, 0x10000
	v_lshrrev_b32_e32 v173, 3, v172
	v_and_b32_e32 v176, 7, v172
	v_lshlrev_b32_e32 v176, 4, v176
	v_mul_u32_u24_e32 v174, 0x90, v173
	v_add3_u32 v174, v174, v176, m0
	v_mul_u32_u24_e32 v175, 0x90, v26
	v_lshrrev_b32_e32 v178, 5, v172
	v_lshl_add_u32 v175, v178, 4, v175
	v_add_u32_e32 v175, m0, v175
	v_lshlrev_b32_e32 v178, 4, v178
	v_sub_u32_e32 v178, v176, v178
	v_sub_u32_e32 v173, v173, v26
	v_lshl_add_u32 v178, v173, 11, v178
	v_subrev_u32_e32 v178, 64, v178
	v_ashrrev_i32_e32 v179, 31, v178
	v_lshl_add_u64 v[142:143], v[22:23], 0, v[178:179]
	v_lshl_add_u64 v[150:151], v[24:25], 0, v[178:179]
	s_mov_b32 s100, 0x4000
	s_mov_b32 s101, 0
	v_lshl_add_u64 v[144:145], v[142:143], 0, s[100:101]
	v_lshl_add_u64 v[146:147], v[144:145], 0, s[100:101]
	v_lshl_add_u64 v[148:149], v[146:147], 0, s[100:101]
	v_lshl_add_u64 v[152:153], v[150:151], 0, s[100:101]
	v_lshl_add_u64 v[154:155], v[152:153], 0, s[100:101]
	v_lshl_add_u64 v[156:157], v[154:155], 0, s[100:101]
	global_load_dwordx4 v[30:33], v[142:143], off
	global_load_dwordx4 v[34:37], v[144:145], off
	global_load_dwordx4 v[38:41], v[146:147], off
	global_load_dwordx4 v[42:45], v[148:149], off
	global_load_dwordx4 v[46:49], v[150:151], off
	global_load_dwordx4 v[50:53], v[152:153], off
	global_load_dwordx4 v[54:57], v[154:155], off
	global_load_dwordx4 v[58:61], v[156:157], off
	global_load_dwordx4 v[62:65], v[142:143], off offset:128
	global_load_dwordx4 v[66:69], v[144:145], off offset:128
	global_load_dwordx4 v[70:73], v[146:147], off offset:128
	global_load_dwordx4 v[74:77], v[148:149], off offset:128
	global_load_dwordx4 v[78:81], v[150:151], off offset:128
	global_load_dwordx4 v[82:85], v[152:153], off offset:128
	global_load_dwordx4 v[86:89], v[154:155], off offset:128
	global_load_dwordx4 v[90:93], v[156:157], off offset:128
	s_waitcnt vmcnt(8)
	ds_write_b128 v174, v[30:33]
	ds_write_b128 v174, v[34:37] offset:1152
	ds_write_b128 v174, v[38:41] offset:2304
	ds_write_b128 v174, v[42:45] offset:3456
	ds_write_b128 v174, v[46:49] offset:4608
	ds_write_b128 v174, v[50:53] offset:5760
	ds_write_b128 v174, v[54:57] offset:6912
	ds_write_b128 v174, v[58:61] offset:8064
	s_waitcnt lgkmcnt(0)
	ds_read_b128 v[110:113], v175
	ds_read_b128 v[126:129], v175 offset:4608
	ds_read_b128 v[114:117], v175 offset:32
	ds_read_b128 v[130:133], v175 offset:4640
	ds_read_b128 v[118:121], v175 offset:64
	ds_read_b128 v[134:137], v175 offset:4672
	ds_read_b128 v[122:125], v175 offset:96
	ds_read_b128 v[138:141], v175 offset:4704
	s_waitcnt lgkmcnt(6)
	v_mfma_f32_32x32x16_bf16 v[0:15], v[110:113], v[126:129], v[0:15]
	s_waitcnt lgkmcnt(4)
	v_mfma_f32_32x32x16_bf16 v[0:15], v[114:117], v[130:133], v[0:15]
	s_waitcnt lgkmcnt(2)
	v_mfma_f32_32x32x16_bf16 v[0:15], v[118:121], v[134:137], v[0:15]
	s_waitcnt lgkmcnt(0)
	v_mfma_f32_32x32x16_bf16 v[0:15], v[122:125], v[138:141], v[0:15]
	s_waitcnt vmcnt(0)
	ds_write_b128 v174, v[62:65]
	ds_write_b128 v174, v[66:69] offset:1152
	ds_write_b128 v174, v[70:73] offset:2304
	ds_write_b128 v174, v[74:77] offset:3456
	ds_write_b128 v174, v[78:81] offset:4608
	ds_write_b128 v174, v[82:85] offset:5760
	ds_write_b128 v174, v[86:89] offset:6912
	ds_write_b128 v174, v[90:93] offset:8064
	s_waitcnt lgkmcnt(0)
	ds_read_b128 v[110:113], v175
	ds_read_b128 v[126:129], v175 offset:4608
	ds_read_b128 v[114:117], v175 offset:32
	ds_read_b128 v[130:133], v175 offset:4640
	ds_read_b128 v[118:121], v175 offset:64
	ds_read_b128 v[134:137], v175 offset:4672
	ds_read_b128 v[122:125], v175 offset:96
	ds_read_b128 v[138:141], v175 offset:4704
	s_waitcnt lgkmcnt(6)
	v_mfma_f32_32x32x16_bf16 v[0:15], v[110:113], v[126:129], v[0:15]
	s_waitcnt lgkmcnt(4)
	v_mfma_f32_32x32x16_bf16 v[0:15], v[114:117], v[130:133], v[0:15]
	s_waitcnt lgkmcnt(2)
	v_mfma_f32_32x32x16_bf16 v[0:15], v[118:121], v[134:137], v[0:15]
	s_waitcnt lgkmcnt(0)
	v_mfma_f32_32x32x16_bf16 v[0:15], v[122:125], v[138:141], v[0:15]
	s_movk_i32 s10, 0x100
	v_add_u32_e32 v22, s13, v27
	s_barrier
	s_nop 8
	ds_write2st64_b32 v22, v0, v1 offset1:1
	ds_write2st64_b32 v22, v2, v3 offset0:2 offset1:3
	ds_write2st64_b32 v22, v4, v5 offset0:4 offset1:5
	ds_write2st64_b32 v22, v6, v7 offset0:6 offset1:7
	ds_write2st64_b32 v22, v8, v9 offset0:8 offset1:9
	ds_write2st64_b32 v22, v10, v11 offset0:10 offset1:11
	ds_write2st64_b32 v22, v12, v13 offset0:12 offset1:13
	ds_write2st64_b32 v22, v14, v15 offset0:14 offset1:15
	v_add_u32_e32 v14, s14, v27
	s_waitcnt lgkmcnt(0)
	s_barrier
	ds_read2st64_b32 v[0:1], v14 offset1:1
	ds_read2st64_b32 v[2:3], v14 offset0:16 offset1:17
	ds_read2st64_b32 v[4:5], v14 offset0:32 offset1:33
	ds_read2st64_b32 v[6:7], v14 offset0:48 offset1:49
	ds_read2st64_b32 v[8:9], v14 offset0:64 offset1:65
	ds_read2st64_b32 v[10:11], v14 offset0:80 offset1:81
	ds_read2st64_b32 v[12:13], v14 offset0:96 offset1:97
	ds_read2st64_b32 v[14:15], v14 offset0:112 offset1:113
	s_waitcnt lgkmcnt(7)
	v_add_f32_e32 v0, 0, v0
	s_waitcnt lgkmcnt(6)
	v_add_f32_e32 v0, v0, v2
	s_waitcnt lgkmcnt(5)
	v_add_f32_e32 v0, v0, v4
	s_waitcnt lgkmcnt(4)
	v_add_f32_e32 v0, v0, v6
	s_waitcnt lgkmcnt(3)
	v_add_f32_e32 v0, v0, v8
	s_waitcnt lgkmcnt(2)
	v_add_f32_e32 v0, v0, v10
	s_waitcnt lgkmcnt(1)
	v_add_f32_e32 v0, v0, v12
	s_waitcnt lgkmcnt(0)
	v_add_f32_e32 v2, v0, v14
	v_add_f32_e32 v0, 0, v1
	v_add_f32_e32 v0, v0, v3
	v_add_f32_e32 v0, v0, v5
	v_add_f32_e32 v0, v0, v7
	s_lshl_b32 s1, s17, 5
	v_add_f32_e32 v0, v0, v9
	s_lshl_b32 s0, s17, 3
	s_and_b32 s1, s1, 0x60
	v_add_f32_e32 v0, v0, v11
	s_andn2_b32 s0, s0, 31
	v_or_b32_e32 v20, s1, v26
	v_add_f32_e32 v0, v0, v13
	v_lshlrev_b32_e32 v20, 11, v20
	v_add_f32_e32 v1, v0, v15
	v_add_u32_e32 v0, s0, v28
	s_add_i32 s12, s12, 1
	s_add_i32 s16, s16, s46
	s_add_i32 s15, s15, s70
	v_cvt_pk_bf16_f32 v4, v2, v1
	v_lshl_add_u64 v[2:3], s[8:9], 0, v[20:21]
	v_ashrrev_i32_e32 v1, 31, v0
	s_cmp_eq_u32 s12, s44
	v_lshl_add_u64 v[0:1], v[0:1], 1, v[2:3]
	s_cselect_b64 s[10:11], -1, 0
	global_store_dword v[0:1], v4, off
	s_branch .LBB0_907

; template <int MODE>
; __device__ __forceinline__ void small_gemm(LAS unsigned char* lds, const bf16* A, const bf16* Bt, int N, int K, bf16* O, int ldc, int act_cols, const float* bias, const bf16* Yv, int ldy, int it0, int it1) {
;     ...
;     for (int it = it0; it < it1; ++it) {
;         const int item = BX + it * GSZ; if (item >= nitems) break;
;         const int rt = item & 3, ct = item >> 2;
;         const int hc = 32 * ct + tl;
;         const int brow = (MODE == 3) ? (256 * (hc >> 7) + (hc & 127)) : hc;
;         const bf16* ap = A + (size_t)(32 * rt + tl) * K + wave * kw + 8 * hh;
;         const bf16* bp = Bt + (size_t)brow * K + wave * kw + 8 * hh;
;         v16f acc0, acc1;
; #pragma unroll
;         for (int r = 0; r < 16; ++r) { acc0[r] = 0.f; acc1[r] = 0.f; }
; #pragma unroll 4
;         for (int ks = 0; ks < nks; ++ks) {
;             const bfx8 a = *(const bfx8*)(ap + 16 * ks);
;             const bfx8 b0 = *(const bfx8*)(bp + 16 * ks);
;             acc0 = __builtin_amdgcn_mfma_f32_32x32x16_bf16(b0, a, acc0, 0, 0, 0);
;             if (MODE == 3) { const bfx8 b1 = *(const bfx8*)(bp + (size_t)128 * K + 16 * ks); acc1 = __builtin_amdgcn_mfma_f32_32x32x16_bf16(b1, a, acc1, 0, 0, 0); }
;         }
;         __syncthreads();
; #pragma unroll
;         for (int r = 0; r < 16; ++r) { red[(wave * 16 + r) * 64 + lane] = acc0[r]; if (MODE == 3) red[8192 + (wave * 16 + r) * 64 + lane] = acc1[r]; }
;         __syncthreads();
;         float v0[2], v1[2];
; #pragma unroll
;         for (int e = 0; e < 2; ++e) { float s0 = 0.f, s1 = 0.f;
; #pragma unroll
;             for (int w = 0; w < 8; ++w) { s0 += red[(w * 16 + 2 * wave + e) * 64 + lane]; if (MODE == 3) s1 += red[8192 + (w * 16 + 2 * wave + e) * 64 + lane]; }
;             v0[e] = s0; v1[e] = s1; }
;         const int reg = 2 * wave;
;         const int col = 32 * ct + (reg & 3) + 8 * (reg >> 2) + 4 * hh;
;         const size_t row = (size_t)(32 * rt + tl);
;         float o0 = v0[0], o1 = v0[1];
;         if (MODE == 1) { if (col < act_cols) { o0 = gelu_t(o0); o1 = gelu_t(o1); } }
;         if (MODE == 2) { const unsigned y = *(const unsigned*)(Yv + row * ldy + col); o0 = bf_lo(y) * pg8::sigmoid_f(o0 + bias[col]); o1 = bf_hi(y) * pg8::sigmoid_f(o1 + bias[col + 1]); }
;         if (MODE == 3) { o0 = pg8::silu_f(o0) * v1[0]; o1 = pg8::silu_f(o1) * v1[1]; }
.LBB0_940:
	v_and_b32_e32 v172, 63, v182
	v_lshrrev_b32_e32 v173, 6, v182
	s_nop 0
	v_readfirstlane_b32 s98, v173
	s_mul_i32 m0, s98, 0x2400
	s_add_i32 m0, m0, 0x10000
	v_lshrrev_b32_e32 v173, 3, v172
	v_and_b32_e32 v176, 7, v172
	v_lshlrev_b32_e32 v176, 4, v176
	v_mul_u32_u24_e32 v174, 0x90, v173
	v_add3_u32 v174, v174, v176, m0
	v_mul_u32_u24_e32 v175, 0x90, v26
	v_lshrrev_b32_e32 v178, 5, v172
	v_lshl_add_u32 v175, v178, 4, v175
	v_add_u32_e32 v175, m0, v175
	v_lshlrev_b32_e32 v178, 4, v178
	v_sub_u32_e32 v178, v176, v178
	v_sub_u32_e32 v173, v173, v26
	v_lshl_add_u32 v178, v173, 11, v178
	v_subrev_u32_e32 v178, 64, v178
	v_ashrrev_i32_e32 v179, 31, v178
	v_lshl_add_u64 v[142:143], v[22:23], 0, v[178:179]
	v_lshl_add_u64 v[150:151], v[24:25], 0, v[178:179]
	s_mov_b32 s100, 0x4000
	s_mov_b32 s101, 0
	v_lshl_add_u64 v[144:145], v[142:143], 0, s[100:101]
	v_lshl_add_u64 v[146:147], v[144:145], 0, s[100:101]
	v_lshl_add_u64 v[148:149], v[146:147], 0, s[100:101]
	v_lshl_add_u64 v[152:153], v[150:151], 0, s[100:101]
	v_lshl_add_u64 v[154:155], v[152:153], 0, s[100:101]
	v_lshl_add_u64 v[156:157], v[154:155], 0, s[100:101]
	global_load_dwordx4 v[30:33], v[142:143], off
	global_load_dwordx4 v[34:37], v[144:145], off
	global_load_dwordx4 v[38:41], v[146:147], off
	global_load_dwordx4 v[42:45], v[148:149], off
	global_load_dwordx4 v[46:49], v[150:151], off
	global_load_dwordx4 v[50:53], v[152:153], off
	global_load_dwordx4 v[54:57], v[154:155], off
	global_load_dwordx4 v[58:61], v[156:157], off
	global_load_dwordx4 v[62:65], v[142:143], off offset:128
	global_load_dwordx4 v[66:69], v[144:145], off offset:128
	global_load_dwordx4 v[70:73], v[146:147], off offset:128
	global_load_dwordx4 v[74:77], v[148:149], off offset:128
	global_load_dwordx4 v[78:81], v[150:151], off offset:128
	global_load_dwordx4 v[82:85], v[152:153], off offset:128
	global_load_dwordx4 v[86:89], v[154:155], off offset:128
	global_load_dwordx4 v[90:93], v[156:157], off offset:128
	s_waitcnt vmcnt(8)
	ds_write_b128 v174, v[30:33]
	ds_write_b128 v174, v[34:37] offset:1152
	ds_write_b128 v174, v[38:41] offset:2304
	ds_write_b128 v174, v[42:45] offset:3456
	ds_write_b128 v174, v[46:49] offset:4608
	ds_write_b128 v174, v[50:53] offset:5760
	ds_write_b128 v174, v[54:57] offset:6912
	ds_write_b128 v174, v[58:61] offset:8064
	s_waitcnt lgkmcnt(0)
	ds_read_b128 v[110:113], v175
	ds_read_b128 v[126:129], v175 offset:4608
	ds_read_b128 v[114:117], v175 offset:32
	ds_read_b128 v[130:133], v175 offset:4640
	ds_read_b128 v[118:121], v175 offset:64
	ds_read_b128 v[134:137], v175 offset:4672
	ds_read_b128 v[122:125], v175 offset:96
	ds_read_b128 v[138:141], v175 offset:4704
	s_waitcnt lgkmcnt(6)
	v_mfma_f32_32x32x16_bf16 v[0:15], v[110:113], v[126:129], v[0:15]
	s_waitcnt lgkmcnt(4)
	v_mfma_f32_32x32x16_bf16 v[0:15], v[114:117], v[130:133], v[0:15]
	s_waitcnt lgkmcnt(2)
	v_mfma_f32_32x32x16_bf16 v[0:15], v[118:121], v[134:137], v[0:15]
	s_waitcnt lgkmcnt(0)
	v_mfma_f32_32x32x16_bf16 v[0:15], v[122:125], v[138:141], v[0:15]
	s_waitcnt vmcnt(0)
	ds_write_b128 v174, v[62:65]
	ds_write_b128 v174, v[66:69] offset:1152
	ds_write_b128 v174, v[70:73] offset:2304
	ds_write_b128 v174, v[74:77] offset:3456
	ds_write_b128 v174, v[78:81] offset:4608
	ds_write_b128 v174, v[82:85] offset:5760
	ds_write_b128 v174, v[86:89] offset:6912
	ds_write_b128 v174, v[90:93] offset:8064
	s_waitcnt lgkmcnt(0)
	ds_read_b128 v[110:113], v175
	ds_read_b128 v[126:129], v175 offset:4608
	ds_read_b128 v[114:117], v175 offset:32
	ds_read_b128 v[130:133], v175 offset:4640
	ds_read_b128 v[118:121], v175 offset:64
	ds_read_b128 v[134:137], v175 offset:4672
	ds_read_b128 v[122:125], v175 offset:96
	ds_read_b128 v[138:141], v175 offset:4704
	s_waitcnt lgkmcnt(6)
	v_mfma_f32_32x32x16_bf16 v[0:15], v[110:113], v[126:129], v[0:15]
	s_waitcnt lgkmcnt(4)
	v_mfma_f32_32x32x16_bf16 v[0:15], v[114:117], v[130:133], v[0:15]
	s_waitcnt lgkmcnt(2)
	v_mfma_f32_32x32x16_bf16 v[0:15], v[118:121], v[134:137], v[0:15]
	s_waitcnt lgkmcnt(0)
	v_mfma_f32_32x32x16_bf16 v[0:15], v[122:125], v[138:141], v[0:15]
	s_movk_i32 s12, 0x100
	v_add_u32_e32 v22, s14, v27
	s_barrier
	s_nop 8
	ds_write2st64_b32 v22, v0, v1 offset1:1
	ds_write2st64_b32 v22, v2, v3 offset0:2 offset1:3
	ds_write2st64_b32 v22, v4, v5 offset0:4 offset1:5
	ds_write2st64_b32 v22, v6, v7 offset0:6 offset1:7
	ds_write2st64_b32 v22, v8, v9 offset0:8 offset1:9
	ds_write2st64_b32 v22, v10, v11 offset0:10 offset1:11
	ds_write2st64_b32 v22, v12, v13 offset0:12 offset1:13
	ds_write2st64_b32 v22, v14, v15 offset0:14 offset1:15
	v_add_u32_e32 v14, s15, v27
	s_waitcnt lgkmcnt(0)
	s_barrier
	ds_read2st64_b32 v[0:1], v14 offset1:1
	ds_read2st64_b32 v[2:3], v14 offset0:16 offset1:17
	ds_read2st64_b32 v[4:5], v14 offset0:32 offset1:33
	ds_read2st64_b32 v[6:7], v14 offset0:48 offset1:49
	ds_read2st64_b32 v[8:9], v14 offset0:64 offset1:65
	ds_read2st64_b32 v[10:11], v14 offset0:80 offset1:81
	ds_read2st64_b32 v[12:13], v14 offset0:96 offset1:97
	ds_read2st64_b32 v[14:15], v14 offset0:112 offset1:113
	s_waitcnt lgkmcnt(7)
	v_add_f32_e32 v0, 0, v0
	s_waitcnt lgkmcnt(6)
	v_add_f32_e32 v0, v0, v2
	s_waitcnt lgkmcnt(5)
	v_add_f32_e32 v0, v0, v4
	s_waitcnt lgkmcnt(4)
	v_add_f32_e32 v0, v0, v6
	s_waitcnt lgkmcnt(3)
	v_add_f32_e32 v0, v0, v8
	s_waitcnt lgkmcnt(2)
	v_add_f32_e32 v0, v0, v10
	s_waitcnt lgkmcnt(1)
	v_add_f32_e32 v0, v0, v12
	s_waitcnt lgkmcnt(0)
	v_add_f32_e32 v2, v0, v14
	v_add_f32_e32 v0, 0, v1
	v_add_f32_e32 v0, v0, v3
	v_add_f32_e32 v0, v0, v5
	v_add_f32_e32 v0, v0, v7
	s_lshl_b32 s1, s19, 5
	v_add_f32_e32 v0, v0, v9
	s_lshl_b32 s0, s19, 3
	s_and_b32 s1, s1, 0x60
	v_add_f32_e32 v0, v0, v11
	s_andn2_b32 s0, s0, 31
	v_or_b32_e32 v20, s1, v26
	v_add_f32_e32 v0, v0, v13
	v_lshlrev_b32_e32 v20, 11, v20
	v_add_f32_e32 v1, v0, v15
	v_add_u32_e32 v0, s0, v28
	s_add_i32 s0, s18, 1
	s_add_i32 s17, s17, s46
	s_add_i32 s16, s16, s70
	v_cvt_pk_bf16_f32 v4, v2, v1
	v_lshl_add_u64 v[2:3], s[10:11], 0, v[20:21]
	v_ashrrev_i32_e32 v1, 31, v0
	s_cmp_gt_u32 s18, 2
	v_lshl_add_u64 v[0:1], v[0:1], 1, v[2:3]
	s_cselect_b64 s[12:13], -1, 0
	s_mov_b32 s18, s0
	global_store_dword v[0:1], v4, off
	s_branch .LBB0_937

; template <int MODE>
; __device__ __forceinline__ void small_gemm(LAS unsigned char* lds, const bf16* A, const bf16* Bt, int N, int K, bf16* O, int ldc, int act_cols, const float* bias, const bf16* Yv, int ldy, int it0, int it1) {
;     ...
;     for (int it = it0; it < it1; ++it) {
;         const int item = BX + it * GSZ; if (item >= nitems) break;
;         const int rt = item & 3, ct = item >> 2;
;         const int hc = 32 * ct + tl;
;         const int brow = (MODE == 3) ? (256 * (hc >> 7) + (hc & 127)) : hc;
;         const bf16* ap = A + (size_t)(32 * rt + tl) * K + wave * kw + 8 * hh;
;         const bf16* bp = Bt + (size_t)brow * K + wave * kw + 8 * hh;
;         v16f acc0, acc1;
; #pragma unroll
;         for (int r = 0; r < 16; ++r) { acc0[r] = 0.f; acc1[r] = 0.f; }
; #pragma unroll 4
;         for (int ks = 0; ks < nks; ++ks) {
;             const bfx8 a = *(const bfx8*)(ap + 16 * ks);
;             const bfx8 b0 = *(const bfx8*)(bp + 16 * ks);
;             acc0 = __builtin_amdgcn_mfma_f32_32x32x16_bf16(b0, a, acc0, 0, 0, 0);
;             if (MODE == 3) { const bfx8 b1 = *(const bfx8*)(bp + (size_t)128 * K + 16 * ks); acc1 = __builtin_amdgcn_mfma_f32_32x32x16_bf16(b1, a, acc1, 0, 0, 0); }
;         }
.LBB0_1107:
	v_and_b32_e32 v70, 63, v182
	v_lshrrev_b32_e32 v71, 6, v182
	s_nop 0
	v_readfirstlane_b32 s98, v71
	s_mul_i32 m0, s98, 0x2400
	s_add_i32 m0, m0, 0x10000
	v_lshrrev_b32_e32 v71, 3, v70
	v_and_b32_e32 v74, 7, v70
	v_lshlrev_b32_e32 v74, 4, v74
	v_mul_u32_u24_e32 v72, 0x90, v71
	v_add3_u32 v72, v72, v74, m0
	v_mul_u32_u24_e32 v73, 0x90, v42
	v_lshrrev_b32_e32 v76, 5, v70
	v_lshl_add_u32 v73, v76, 4, v73
	v_add_u32_e32 v73, m0, v73
	v_lshlrev_b32_e32 v76, 4, v76
	v_sub_u32_e32 v76, v74, v76
	v_sub_u32_e32 v71, v71, v42
	v_lshl_add_u32 v76, v71, 11, v76
	v_ashrrev_i32_e32 v77, 31, v76
	v_lshl_add_u64 v[78:79], v[38:39], 0, v[76:77]
	v_add_co_u32_e32 v54, vcc, s17, v78
	s_nop 1
	v_addc_co_u32_e32 v55, vcc, 0, v79, vcc
	v_add_co_u32_e32 v62, vcc, s18, v78
	s_nop 1
	v_addc_co_u32_e32 v63, vcc, 0, v79, vcc
	v_subrev_u32_e32 v76, 64, v76
	v_ashrrev_i32_e32 v77, 31, v76
	v_lshl_add_u64 v[46:47], v[40:41], 0, v[76:77]
	s_mov_b32 s100, 0x4000
	s_mov_b32 s101, 0
	v_lshl_add_u64 v[48:49], v[46:47], 0, s[100:101]
	v_lshl_add_u64 v[50:51], v[48:49], 0, s[100:101]
	v_lshl_add_u64 v[52:53], v[50:51], 0, s[100:101]
	v_lshl_add_u64 v[56:57], v[54:55], 0, s[100:101]
	v_lshl_add_u64 v[58:59], v[56:57], 0, s[100:101]
	v_lshl_add_u64 v[60:61], v[58:59], 0, s[100:101]
	v_lshl_add_u64 v[64:65], v[62:63], 0, s[100:101]
	v_lshl_add_u64 v[66:67], v[64:65], 0, s[100:101]
	v_lshl_add_u64 v[68:69], v[66:67], 0, s[100:101]
	global_load_dwordx4 v[80:83], v[46:47], off
	global_load_dwordx4 v[84:87], v[48:49], off
	global_load_dwordx4 v[88:91], v[50:51], off
	global_load_dwordx4 v[92:95], v[52:53], off
	global_load_dwordx4 v[96:99], v[54:55], off
	global_load_dwordx4 v[100:103], v[56:57], off
	global_load_dwordx4 v[104:107], v[58:59], off
	global_load_dwordx4 v[108:111], v[60:61], off
	global_load_dwordx4 v[112:115], v[62:63], off
	global_load_dwordx4 v[116:119], v[64:65], off
	global_load_dwordx4 v[120:123], v[66:67], off
	global_load_dwordx4 v[124:127], v[68:69], off
	global_load_dwordx4 v[128:131], v[46:47], off offset:128
	global_load_dwordx4 v[132:135], v[48:49], off offset:128
	global_load_dwordx4 v[136:139], v[50:51], off offset:128
	global_load_dwordx4 v[140:143], v[52:53], off offset:128
	global_load_dwordx4 v[144:147], v[54:55], off offset:128
	global_load_dwordx4 v[148:151], v[56:57], off offset:128
	global_load_dwordx4 v[152:155], v[58:59], off offset:128
	global_load_dwordx4 v[156:159], v[60:61], off offset:128
	global_load_dwordx4 v[160:163], v[62:63], off offset:128
	global_load_dwordx4 v[164:167], v[64:65], off offset:128
	global_load_dwordx4 v[168:171], v[66:67], off offset:128
	global_load_dwordx4 v[172:175], v[68:69], off offset:128
	s_waitcnt vmcnt(12)
	ds_write_b128 v72, v[80:83]
	ds_write_b128 v72, v[84:87] offset:1152
	ds_write_b128 v72, v[88:91] offset:2304
	ds_write_b128 v72, v[92:95] offset:3456
	ds_write_b128 v72, v[96:99] offset:4608
	ds_write_b128 v72, v[100:103] offset:5760
	ds_write_b128 v72, v[104:107] offset:6912
	ds_write_b128 v72, v[108:111] offset:8064
	s_waitcnt lgkmcnt(0)
	ds_read_b128 v[192:195], v73
	ds_read_b128 v[208:211], v73 offset:4608
	ds_read_b128 v[196:199], v73 offset:32
	ds_read_b128 v[212:215], v73 offset:4640
	ds_read_b128 v[200:203], v73 offset:64
	ds_read_b128 v[216:219], v73 offset:4672
	ds_read_b128 v[204:207], v73 offset:96
	ds_read_b128 v[220:223], v73 offset:4704
	s_waitcnt lgkmcnt(6)
	v_mfma_f32_32x32x16_bf16 v[0:15], v[208:211], v[192:195], v[0:15]
	s_waitcnt lgkmcnt(4)
	v_mfma_f32_32x32x16_bf16 v[0:15], v[212:215], v[196:199], v[0:15]
	s_waitcnt lgkmcnt(2)
	v_mfma_f32_32x32x16_bf16 v[0:15], v[216:219], v[200:203], v[0:15]
	s_waitcnt lgkmcnt(0)
	v_mfma_f32_32x32x16_bf16 v[0:15], v[220:223], v[204:207], v[0:15]
	ds_write_b128 v72, v[112:115] offset:4608
	ds_write_b128 v72, v[116:119] offset:5760
	ds_write_b128 v72, v[120:123] offset:6912
	ds_write_b128 v72, v[124:127] offset:8064
	s_waitcnt lgkmcnt(0)
	ds_read_b128 v[208:211], v73 offset:4608
	ds_read_b128 v[212:215], v73 offset:4640
	ds_read_b128 v[216:219], v73 offset:4672
	ds_read_b128 v[220:223], v73 offset:4704
	s_waitcnt lgkmcnt(3)
	v_mfma_f32_32x32x16_bf16 v[16:31], v[208:211], v[192:195], v[16:31]
	s_waitcnt lgkmcnt(2)
	v_mfma_f32_32x32x16_bf16 v[16:31], v[212:215], v[196:199], v[16:31]
	s_waitcnt lgkmcnt(1)
	v_mfma_f32_32x32x16_bf16 v[16:31], v[216:219], v[200:203], v[16:31]
	s_waitcnt lgkmcnt(0)
	v_mfma_f32_32x32x16_bf16 v[16:31], v[220:223], v[204:207], v[16:31]
	s_waitcnt vmcnt(0)
	s_waitcnt lgkmcnt(0)
	ds_write_b128 v72, v[128:131]
	ds_write_b128 v72, v[132:135] offset:1152
	ds_write_b128 v72, v[136:139] offset:2304
	ds_write_b128 v72, v[140:143] offset:3456
	ds_write_b128 v72, v[144:147] offset:4608
	ds_write_b128 v72, v[148:151] offset:5760
	ds_write_b128 v72, v[152:155] offset:6912
	ds_write_b128 v72, v[156:159] offset:8064
	s_waitcnt lgkmcnt(0)
	ds_read_b128 v[192:195], v73
	ds_read_b128 v[208:211], v73 offset:4608
	ds_read_b128 v[196:199], v73 offset:32
	ds_read_b128 v[212:215], v73 offset:4640
	ds_read_b128 v[200:203], v73 offset:64
	ds_read_b128 v[216:219], v73 offset:4672
	ds_read_b128 v[204:207], v73 offset:96
	ds_read_b128 v[220:223], v73 offset:4704
	s_waitcnt lgkmcnt(6)
	v_mfma_f32_32x32x16_bf16 v[0:15], v[208:211], v[192:195], v[0:15]
	s_waitcnt lgkmcnt(4)
	v_mfma_f32_32x32x16_bf16 v[0:15], v[212:215], v[196:199], v[0:15]
	s_waitcnt lgkmcnt(2)
	v_mfma_f32_32x32x16_bf16 v[0:15], v[216:219], v[200:203], v[0:15]
	s_waitcnt lgkmcnt(0)
	v_mfma_f32_32x32x16_bf16 v[0:15], v[220:223], v[204:207], v[0:15]
	ds_write_b128 v72, v[160:163] offset:4608
	ds_write_b128 v72, v[164:167] offset:5760
	ds_write_b128 v72, v[168:171] offset:6912
	ds_write_b128 v72, v[172:175] offset:8064
	s_waitcnt lgkmcnt(0)
	ds_read_b128 v[208:211], v73 offset:4608
	ds_read_b128 v[212:215], v73 offset:4640
	ds_read_b128 v[216:219], v73 offset:4672
	ds_read_b128 v[220:223], v73 offset:4704
	s_waitcnt lgkmcnt(3)
	v_mfma_f32_32x32x16_bf16 v[16:31], v[208:211], v[192:195], v[16:31]
	s_waitcnt lgkmcnt(2)
	v_mfma_f32_32x32x16_bf16 v[16:31], v[212:215], v[196:199], v[16:31]
	s_waitcnt lgkmcnt(1)
	v_mfma_f32_32x32x16_bf16 v[16:31], v[216:219], v[200:203], v[16:31]
	s_waitcnt lgkmcnt(0)
	v_mfma_f32_32x32x16_bf16 v[16:31], v[220:223], v[204:207], v[16:31]
	s_movk_i32 s12, 0x100
	s_barrier
; __device__ __forceinline__ unsigned cvt_pk_bf16(float lo, float hi) { unsigned r; asm volatile("v_cvt_pk_bf16_f32 %0, %1, %2" : "=v"(r) : "v"(lo), "v"(hi)); return r; }
; __device__ __forceinline__ float bf_lo(unsigned w) { return __uint_as_float(w << 16); }
; __device__ __forceinline__ float bf_hi(unsigned w) { return __uint_as_float(w & 0xffff0000u); }
; __device__ __forceinline__ float gelu_t(float x) { const float u = 1.5957691216057308f * (x + 0.044715f * x * x * x); return x * sigmoid_f(u); }
; __device__ __forceinline__ float sigmoid_f(float x) { return __builtin_amdgcn_rcpf(1.0f + __expf(-x)); }
; __device__ __forceinline__ float silu_f(float x) { return x * sigmoid_f(x); }
; template <int MODE>
; __device__ __forceinline__ void small_gemm(LAS unsigned char* lds, const bf16* A, const bf16* Bt, int N, int K, bf16* O, int ldc, int act_cols, const float* bias, const bf16* Yv, int ldy, int it0, int it1) {
;     ...
;         __syncthreads();
; #pragma unroll
;         for (int r = 0; r < 16; ++r) { red[(wave * 16 + r) * 64 + lane] = acc0[r]; if (MODE == 3) red[8192 + (wave * 16 + r) * 64 + lane] = acc1[r]; }
;         __syncthreads();
;         float v0[2], v1[2];
; #pragma unroll
;         for (int e = 0; e < 2; ++e) { float s0 = 0.f, s1 = 0.f;
; #pragma unroll
;             for (int w = 0; w < 8; ++w) { s0 += red[(w * 16 + 2 * wave + e) * 64 + lane]; if (MODE == 3) s1 += red[8192 + (w * 16 + 2 * wave + e) * 64 + lane]; }
;             v0[e] = s0; v1[e] = s1; }
;         const int reg = 2 * wave;
;         const int col = 32 * ct + (reg & 3) + 8 * (reg >> 2) + 4 * hh;
;         const size_t row = (size_t)(32 * rt + tl);
;         float o0 = v0[0], o1 = v0[1];
;         if (MODE == 1) { if (col < act_cols) { o0 = gelu_t(o0); o1 = gelu_t(o1); } }
;         if (MODE == 2) { const unsigned y = *(const unsigned*)(Yv + row * ldy + col); o0 = bf_lo(y) * pg8::sigmoid_f(o0 + bias[col]); o1 = bf_hi(y) * pg8::sigmoid_f(o1 + bias[col + 1]); }
;         if (MODE == 3) { o0 = pg8::silu_f(o0) * v1[0]; o1 = pg8::silu_f(o1) * v1[1]; }
;         *(unsigned*)(O + row * ldc + col) = cvt_pk_bf16(o0, o1);
	s_nop 7
	ds_write2st64_b32 v45, v0, v1 offset1:1
	s_nop 0
	ds_write2st64_b32 v45, v16, v17 offset0:128 offset1:129
	ds_write2st64_b32 v45, v2, v3 offset0:2 offset1:3
	ds_write2st64_b32 v45, v18, v19 offset0:130 offset1:131
	ds_write2st64_b32 v45, v4, v5 offset0:4 offset1:5
	ds_write2st64_b32 v45, v20, v21 offset0:132 offset1:133
	ds_write2st64_b32 v45, v6, v7 offset0:6 offset1:7
	ds_write2st64_b32 v45, v22, v23 offset0:134 offset1:135
	ds_write2st64_b32 v45, v8, v9 offset0:8 offset1:9
	ds_write2st64_b32 v45, v24, v25 offset0:136 offset1:137
	ds_write2st64_b32 v45, v10, v11 offset0:10 offset1:11
	ds_write2st64_b32 v45, v26, v27 offset0:138 offset1:139
	ds_write2st64_b32 v45, v12, v13 offset0:12 offset1:13
	ds_write2st64_b32 v45, v28, v29 offset0:140 offset1:141
	ds_write2st64_b32 v45, v14, v15 offset0:14 offset1:15
	ds_write2st64_b32 v45, v30, v31 offset0:142 offset1:143
	s_waitcnt lgkmcnt(0)
	s_barrier
	ds_read2st64_b32 v[0:1], v44 offset1:1
	ds_read2st64_b32 v[2:3], v44 offset0:16 offset1:17
	ds_read2st64_b32 v[4:5], v44 offset0:32 offset1:33
	ds_read2st64_b32 v[6:7], v44 offset0:48 offset1:49
	ds_read2st64_b32 v[8:9], v44 offset0:128 offset1:129
	ds_read2st64_b32 v[10:11], v44 offset0:144 offset1:145
	ds_read2st64_b32 v[12:13], v44 offset0:160 offset1:161
	ds_read2st64_b32 v[14:15], v44 offset0:176 offset1:177
	ds_read2st64_b32 v[16:17], v44 offset0:64 offset1:65
	ds_read2st64_b32 v[18:19], v44 offset0:80 offset1:81
	ds_read2st64_b32 v[20:21], v44 offset0:96 offset1:97
	ds_read2st64_b32 v[22:23], v44 offset0:112 offset1:113
	ds_read2st64_b32 v[24:25], v44 offset0:192 offset1:193
	ds_read2st64_b32 v[26:27], v44 offset0:208 offset1:209
	ds_read2st64_b32 v[28:29], v44 offset0:224 offset1:225
	ds_read2st64_b32 v[30:31], v44 offset0:240 offset1:241
	s_waitcnt lgkmcnt(11)
	v_mov_b32_e32 v38, v8
	v_mov_b32_e32 v39, v0
	v_pk_add_f32 v[38:39], v[38:39], 0 op_sel_hi:[1,0]
	s_waitcnt lgkmcnt(10)
	v_mov_b32_e32 v40, v10
	v_mov_b32_e32 v41, v2
	v_mov_b32_e32 v0, v9
	v_pk_add_f32 v[38:39], v[38:39], v[40:41]
	s_waitcnt lgkmcnt(9)
	v_mov_b32_e32 v40, v12
	v_mov_b32_e32 v41, v4
	v_pk_add_f32 v[0:1], v[0:1], 0 op_sel_hi:[1,0]
	v_mov_b32_e32 v2, v11
	v_pk_add_f32 v[38:39], v[38:39], v[40:41]
	s_waitcnt lgkmcnt(8)
	v_mov_b32_e32 v40, v14
	v_mov_b32_e32 v41, v6
	v_pk_add_f32 v[0:1], v[0:1], v[2:3]
	v_mov_b32_e32 v4, v13
	v_pk_add_f32 v[38:39], v[38:39], v[40:41]
	s_waitcnt lgkmcnt(3)
	v_mov_b32_e32 v40, v24
	v_mov_b32_e32 v41, v16
	v_pk_add_f32 v[0:1], v[0:1], v[4:5]
	v_mov_b32_e32 v6, v15
	v_pk_add_f32 v[38:39], v[38:39], v[40:41]
	s_waitcnt lgkmcnt(2)
	v_mov_b32_e32 v40, v26
	v_mov_b32_e32 v41, v18
	v_pk_add_f32 v[0:1], v[0:1], v[6:7]
	v_mov_b32_e32 v16, v25
	v_pk_add_f32 v[38:39], v[38:39], v[40:41]
	s_waitcnt lgkmcnt(1)
	v_mov_b32_e32 v40, v28
	v_mov_b32_e32 v41, v20
	v_pk_add_f32 v[0:1], v[0:1], v[16:17]
	v_mov_b32_e32 v18, v27
	v_pk_add_f32 v[38:39], v[38:39], v[40:41]
	s_waitcnt lgkmcnt(0)
	v_mov_b32_e32 v40, v30
	v_mov_b32_e32 v41, v22
	v_pk_add_f32 v[0:1], v[0:1], v[18:19]
	v_mov_b32_e32 v20, v29
	v_pk_add_f32 v[38:39], v[38:39], v[40:41]
	v_pk_add_f32 v[0:1], v[0:1], v[20:21]
	v_mov_b32_e32 v22, v31
	v_pk_add_f32 v[0:1], v[0:1], v[22:23]
	v_mul_f32_e32 v2, 0xbfb8aa3b, v39
	v_exp_f32_e32 v2, v2
	v_mul_f32_e32 v3, 0xbfb8aa3b, v1
	v_exp_f32_e32 v3, v3
	s_lshl_b32 s0, s21, 3
	v_add_f32_e32 v2, 1.0, v2
	v_rcp_f32_e32 v4, v2
	v_add_f32_e32 v2, 1.0, v3
	v_rcp_f32_e32 v3, v2
	s_andn2_b32 s0, s0, 31
	v_mul_f32_e32 v4, v39, v4
	v_mul_f32_e32 v4, v38, v4
	v_mul_f32_e32 v1, v1, v3
	v_mul_f32_e32 v0, v0, v1
	v_add_u32_e32 v2, s0, v43
	v_cvt_pk_bf16_f32 v4, v4, v0
	v_mov_b64_e32 v[0:1], s[10:11]
	s_add_i32 s14, s14, 1
	s_add_i32 s15, s15, s70
	s_add_i32 s20, s20, s46
	s_add_i32 s16, s16, s71
	v_mad_u64_u32 v[0:1], s[0:1], v36, s19, v[0:1]
	v_ashrrev_i32_e32 v3, 31, v2
	s_cmp_eq_u32 s14, s44
	v_lshl_add_u64 v[0:1], v[2:3], 1, v[0:1]
	s_cselect_b64 s[12:13], -1, 0
	global_store_dword v[0:1], v4, off
	s_branch .LBB0_1104

; template <int MODE>
; __device__ __forceinline__ void small_gemm(LAS unsigned char* lds, const bf16* A, const bf16* Bt, int N, int K, bf16* O, int ldc, int act_cols, const float* bias, const bf16* Yv, int ldy, int it0, int it1) {
;     ...
;         const bf16* ap = A + (size_t)(32 * rt + tl) * K + wave * kw + 8 * hh;
;         const bf16* bp = Bt + (size_t)brow * K + wave * kw + 8 * hh;
;         v16f acc0, acc1;
; #pragma unroll
;         for (int r = 0; r < 16; ++r) { acc0[r] = 0.f; acc1[r] = 0.f; }
; #pragma unroll 4
;         for (int ks = 0; ks < nks; ++ks) {
;             const bfx8 a = *(const bfx8*)(ap + 16 * ks);
;             const bfx8 b0 = *(const bfx8*)(bp + 16 * ks);
;             acc0 = __builtin_amdgcn_mfma_f32_32x32x16_bf16(b0, a, acc0, 0, 0, 0);
;             if (MODE == 3) { const bfx8 b1 = *(const bfx8*)(bp + (size_t)128 * K + 16 * ks); acc1 = __builtin_amdgcn_mfma_f32_32x32x16_bf16(b1, a, acc1, 0, 0, 0); }
;         }
.LBB0_1129:
	v_and_b32_e32 v70, 63, v182
	v_lshrrev_b32_e32 v71, 6, v182
	s_nop 0
	v_readfirstlane_b32 s98, v71
	s_mul_i32 m0, s98, 0x2400
	s_add_i32 m0, m0, 0x10000
	v_lshrrev_b32_e32 v71, 3, v70
	v_and_b32_e32 v74, 7, v70
	v_lshlrev_b32_e32 v74, 4, v74
	v_mul_u32_u24_e32 v72, 0x90, v71
	v_add3_u32 v72, v72, v74, m0
	v_mul_u32_u24_e32 v73, 0x90, v42
	v_lshrrev_b32_e32 v76, 5, v70
	v_lshl_add_u32 v73, v76, 4, v73
	v_add_u32_e32 v73, m0, v73
	v_lshlrev_b32_e32 v76, 4, v76
	v_sub_u32_e32 v76, v74, v76
	v_sub_u32_e32 v71, v71, v42
	v_lshl_add_u32 v76, v71, 11, v76
	v_ashrrev_i32_e32 v77, 31, v76
	v_lshl_add_u64 v[78:79], v[38:39], 0, v[76:77]
	v_add_co_u32_e32 v54, vcc, s14, v78
	s_nop 1
	v_addc_co_u32_e32 v55, vcc, 0, v79, vcc
	v_add_co_u32_e32 v62, vcc, s15, v78
	s_nop 1
	v_addc_co_u32_e32 v63, vcc, 0, v79, vcc
	v_subrev_u32_e32 v76, 64, v76
	v_ashrrev_i32_e32 v77, 31, v76
	v_lshl_add_u64 v[46:47], v[40:41], 0, v[76:77]
	s_mov_b32 s100, 0x4000
	s_mov_b32 s101, 0
	v_lshl_add_u64 v[48:49], v[46:47], 0, s[100:101]
	v_lshl_add_u64 v[50:51], v[48:49], 0, s[100:101]
	v_lshl_add_u64 v[52:53], v[50:51], 0, s[100:101]
	v_lshl_add_u64 v[56:57], v[54:55], 0, s[100:101]
	v_lshl_add_u64 v[58:59], v[56:57], 0, s[100:101]
	v_lshl_add_u64 v[60:61], v[58:59], 0, s[100:101]
	v_lshl_add_u64 v[64:65], v[62:63], 0, s[100:101]
	v_lshl_add_u64 v[66:67], v[64:65], 0, s[100:101]
	v_lshl_add_u64 v[68:69], v[66:67], 0, s[100:101]
	global_load_dwordx4 v[80:83], v[46:47], off
	global_load_dwordx4 v[84:87], v[48:49], off
	global_load_dwordx4 v[88:91], v[50:51], off
	global_load_dwordx4 v[92:95], v[52:53], off
	global_load_dwordx4 v[96:99], v[54:55], off
	global_load_dwordx4 v[100:103], v[56:57], off
	global_load_dwordx4 v[104:107], v[58:59], off
	global_load_dwordx4 v[108:111], v[60:61], off
	global_load_dwordx4 v[112:115], v[62:63], off
	global_load_dwordx4 v[116:119], v[64:65], off
	global_load_dwordx4 v[120:123], v[66:67], off
	global_load_dwordx4 v[124:127], v[68:69], off
	global_load_dwordx4 v[128:131], v[46:47], off offset:128
	global_load_dwordx4 v[132:135], v[48:49], off offset:128
	global_load_dwordx4 v[136:139], v[50:51], off offset:128
	global_load_dwordx4 v[140:143], v[52:53], off offset:128
	global_load_dwordx4 v[144:147], v[54:55], off offset:128
	global_load_dwordx4 v[148:151], v[56:57], off offset:128
	global_load_dwordx4 v[152:155], v[58:59], off offset:128
	global_load_dwordx4 v[156:159], v[60:61], off offset:128
	global_load_dwordx4 v[160:163], v[62:63], off offset:128
	global_load_dwordx4 v[164:167], v[64:65], off offset:128
	global_load_dwordx4 v[168:171], v[66:67], off offset:128
	global_load_dwordx4 v[172:175], v[68:69], off offset:128
	s_waitcnt vmcnt(12)
	ds_write_b128 v72, v[80:83]
	ds_write_b128 v72, v[84:87] offset:1152
	ds_write_b128 v72, v[88:91] offset:2304
	ds_write_b128 v72, v[92:95] offset:3456
	ds_write_b128 v72, v[96:99] offset:4608
	ds_write_b128 v72, v[100:103] offset:5760
	ds_write_b128 v72, v[104:107] offset:6912
	ds_write_b128 v72, v[108:111] offset:8064
	s_waitcnt lgkmcnt(0)
	ds_read_b128 v[192:195], v73
	ds_read_b128 v[208:211], v73 offset:4608
	ds_read_b128 v[196:199], v73 offset:32
	ds_read_b128 v[212:215], v73 offset:4640
	ds_read_b128 v[200:203], v73 offset:64
	ds_read_b128 v[216:219], v73 offset:4672
	ds_read_b128 v[204:207], v73 offset:96
	ds_read_b128 v[220:223], v73 offset:4704
	s_waitcnt lgkmcnt(6)
	v_mfma_f32_32x32x16_bf16 v[0:15], v[208:211], v[192:195], v[0:15]
	s_waitcnt lgkmcnt(4)
	v_mfma_f32_32x32x16_bf16 v[0:15], v[212:215], v[196:199], v[0:15]
	s_waitcnt lgkmcnt(2)
	v_mfma_f32_32x32x16_bf16 v[0:15], v[216:219], v[200:203], v[0:15]
	s_waitcnt lgkmcnt(0)
	v_mfma_f32_32x32x16_bf16 v[0:15], v[220:223], v[204:207], v[0:15]
	ds_write_b128 v72, v[112:115] offset:4608
	ds_write_b128 v72, v[116:119] offset:5760
	ds_write_b128 v72, v[120:123] offset:6912
	ds_write_b128 v72, v[124:127] offset:8064
	s_waitcnt lgkmcnt(0)
	ds_read_b128 v[208:211], v73 offset:4608
	ds_read_b128 v[212:215], v73 offset:4640
	ds_read_b128 v[216:219], v73 offset:4672
	ds_read_b128 v[220:223], v73 offset:4704
	s_waitcnt lgkmcnt(3)
	v_mfma_f32_32x32x16_bf16 v[16:31], v[208:211], v[192:195], v[16:31]
	s_waitcnt lgkmcnt(2)
	v_mfma_f32_32x32x16_bf16 v[16:31], v[212:215], v[196:199], v[16:31]
	s_waitcnt lgkmcnt(1)
	v_mfma_f32_32x32x16_bf16 v[16:31], v[216:219], v[200:203], v[16:31]
	s_waitcnt lgkmcnt(0)
	v_mfma_f32_32x32x16_bf16 v[16:31], v[220:223], v[204:207], v[16:31]
	s_waitcnt vmcnt(0)
	s_waitcnt lgkmcnt(0)
	ds_write_b128 v72, v[128:131]
	ds_write_b128 v72, v[132:135] offset:1152
	ds_write_b128 v72, v[136:139] offset:2304
	ds_write_b128 v72, v[140:143] offset:3456
	ds_write_b128 v72, v[144:147] offset:4608
	ds_write_b128 v72, v[148:151] offset:5760
	ds_write_b128 v72, v[152:155] offset:6912
	ds_write_b128 v72, v[156:159] offset:8064
	s_waitcnt lgkmcnt(0)
	ds_read_b128 v[192:195], v73
	ds_read_b128 v[208:211], v73 offset:4608
	ds_read_b128 v[196:199], v73 offset:32
	ds_read_b128 v[212:215], v73 offset:4640
	ds_read_b128 v[200:203], v73 offset:64
	ds_read_b128 v[216:219], v73 offset:4672
	ds_read_b128 v[204:207], v73 offset:96
	ds_read_b128 v[220:223], v73 offset:4704
	s_waitcnt lgkmcnt(6)
	v_mfma_f32_32x32x16_bf16 v[0:15], v[208:211], v[192:195], v[0:15]
	s_waitcnt lgkmcnt(4)
	v_mfma_f32_32x32x16_bf16 v[0:15], v[212:215], v[196:199], v[0:15]
	s_waitcnt lgkmcnt(2)
	v_mfma_f32_32x32x16_bf16 v[0:15], v[216:219], v[200:203], v[0:15]
	s_waitcnt lgkmcnt(0)
	v_mfma_f32_32x32x16_bf16 v[0:15], v[220:223], v[204:207], v[0:15]
	ds_write_b128 v72, v[160:163] offset:4608
	ds_write_b128 v72, v[164:167] offset:5760
	ds_write_b128 v72, v[168:171] offset:6912
	ds_write_b128 v72, v[172:175] offset:8064
	s_waitcnt lgkmcnt(0)
	ds_read_b128 v[208:211], v73 offset:4608
	ds_read_b128 v[212:215], v73 offset:4640
	ds_read_b128 v[216:219], v73 offset:4672
	ds_read_b128 v[220:223], v73 offset:4704
	s_waitcnt lgkmcnt(3)
	v_mfma_f32_32x32x16_bf16 v[16:31], v[208:211], v[192:195], v[16:31]
	s_waitcnt lgkmcnt(2)
	v_mfma_f32_32x32x16_bf16 v[16:31], v[212:215], v[196:199], v[16:31]
	s_waitcnt lgkmcnt(1)
	v_mfma_f32_32x32x16_bf16 v[16:31], v[216:219], v[200:203], v[16:31]
	s_waitcnt lgkmcnt(0)
	v_mfma_f32_32x32x16_bf16 v[16:31], v[220:223], v[204:207], v[16:31]
	s_movk_i32 s12, 0x100
	s_barrier
; __device__ __forceinline__ unsigned cvt_pk_bf16(float lo, float hi) { unsigned r; asm volatile("v_cvt_pk_bf16_f32 %0, %1, %2" : "=v"(r) : "v"(lo), "v"(hi)); return r; }
; __device__ __forceinline__ float bf_lo(unsigned w) { return __uint_as_float(w << 16); }
; __device__ __forceinline__ float bf_hi(unsigned w) { return __uint_as_float(w & 0xffff0000u); }
; __device__ __forceinline__ float sigmoid_f(float x) { return __builtin_amdgcn_rcpf(1.0f + __expf(-x)); }
; __device__ __forceinline__ float silu_f(float x) { return x * sigmoid_f(x); }
; __device__ __forceinline__ float gelu_t(float x) { const float u = 1.5957691216057308f * (x + 0.044715f * x * x * x); return x * sigmoid_f(u); }
; template <int MODE>
; __device__ __forceinline__ void small_gemm(LAS unsigned char* lds, const bf16* A, const bf16* Bt, int N, int K, bf16* O, int ldc, int act_cols, const float* bias, const bf16* Yv, int ldy, int it0, int it1) {
;     ...
;         __syncthreads();
; #pragma unroll
;         for (int r = 0; r < 16; ++r) { red[(wave * 16 + r) * 64 + lane] = acc0[r]; if (MODE == 3) red[8192 + (wave * 16 + r) * 64 + lane] = acc1[r]; }
;         __syncthreads();
;         float v0[2], v1[2];
; #pragma unroll
;         for (int e = 0; e < 2; ++e) { float s0 = 0.f, s1 = 0.f;
; #pragma unroll
;             for (int w = 0; w < 8; ++w) { s0 += red[(w * 16 + 2 * wave + e) * 64 + lane]; if (MODE == 3) s1 += red[8192 + (w * 16 + 2 * wave + e) * 64 + lane]; }
;             v0[e] = s0; v1[e] = s1; }
;         const int reg = 2 * wave;
;         const int col = 32 * ct + (reg & 3) + 8 * (reg >> 2) + 4 * hh;
;         const size_t row = (size_t)(32 * rt + tl);
;         float o0 = v0[0], o1 = v0[1];
;         if (MODE == 1) { if (col < act_cols) { o0 = gelu_t(o0); o1 = gelu_t(o1); } }
;         if (MODE == 2) { const unsigned y = *(const unsigned*)(Yv + row * ldy + col); o0 = bf_lo(y) * pg8::sigmoid_f(o0 + bias[col]); o1 = bf_hi(y) * pg8::sigmoid_f(o1 + bias[col + 1]); }
;         if (MODE == 3) { o0 = pg8::silu_f(o0) * v1[0]; o1 = pg8::silu_f(o1) * v1[1]; }
;         *(unsigned*)(O + row * ldc + col) = cvt_pk_bf16(o0, o1);
;     }
	s_nop 7
	ds_write2st64_b32 v45, v0, v1 offset1:1
	s_nop 0
	ds_write2st64_b32 v45, v16, v17 offset0:128 offset1:129
	ds_write2st64_b32 v45, v2, v3 offset0:2 offset1:3
	ds_write2st64_b32 v45, v18, v19 offset0:130 offset1:131
	ds_write2st64_b32 v45, v4, v5 offset0:4 offset1:5
	ds_write2st64_b32 v45, v20, v21 offset0:132 offset1:133
	ds_write2st64_b32 v45, v6, v7 offset0:6 offset1:7
	ds_write2st64_b32 v45, v22, v23 offset0:134 offset1:135
	ds_write2st64_b32 v45, v8, v9 offset0:8 offset1:9
	ds_write2st64_b32 v45, v24, v25 offset0:136 offset1:137
	ds_write2st64_b32 v45, v10, v11 offset0:10 offset1:11
	ds_write2st64_b32 v45, v26, v27 offset0:138 offset1:139
	ds_write2st64_b32 v45, v12, v13 offset0:12 offset1:13
	ds_write2st64_b32 v45, v28, v29 offset0:140 offset1:141
	ds_write2st64_b32 v45, v14, v15 offset0:14 offset1:15
	ds_write2st64_b32 v45, v30, v31 offset0:142 offset1:143
	s_waitcnt lgkmcnt(0)
	s_barrier
	ds_read2st64_b32 v[0:1], v44 offset1:1
	ds_read2st64_b32 v[2:3], v44 offset0:16 offset1:17
	ds_read2st64_b32 v[4:5], v44 offset0:32 offset1:33
	ds_read2st64_b32 v[6:7], v44 offset0:48 offset1:49
	ds_read2st64_b32 v[8:9], v44 offset0:128 offset1:129
	ds_read2st64_b32 v[10:11], v44 offset0:144 offset1:145
	ds_read2st64_b32 v[12:13], v44 offset0:160 offset1:161
	ds_read2st64_b32 v[14:15], v44 offset0:176 offset1:177
	ds_read2st64_b32 v[16:17], v44 offset0:64 offset1:65
	ds_read2st64_b32 v[18:19], v44 offset0:80 offset1:81
	ds_read2st64_b32 v[20:21], v44 offset0:96 offset1:97
	ds_read2st64_b32 v[22:23], v44 offset0:112 offset1:113
	ds_read2st64_b32 v[24:25], v44 offset0:192 offset1:193
	ds_read2st64_b32 v[26:27], v44 offset0:208 offset1:209
	ds_read2st64_b32 v[28:29], v44 offset0:224 offset1:225
	ds_read2st64_b32 v[30:31], v44 offset0:240 offset1:241
	s_waitcnt lgkmcnt(11)
	v_mov_b32_e32 v38, v8
	v_mov_b32_e32 v39, v0
	v_pk_add_f32 v[38:39], v[38:39], 0 op_sel_hi:[1,0]
	s_waitcnt lgkmcnt(10)
	v_mov_b32_e32 v40, v10
	v_mov_b32_e32 v41, v2
	v_mov_b32_e32 v0, v9
	v_pk_add_f32 v[38:39], v[38:39], v[40:41]
	s_waitcnt lgkmcnt(9)
	v_mov_b32_e32 v40, v12
	v_mov_b32_e32 v41, v4
	v_pk_add_f32 v[0:1], v[0:1], 0 op_sel_hi:[1,0]
	v_mov_b32_e32 v2, v11
	v_pk_add_f32 v[38:39], v[38:39], v[40:41]
	s_waitcnt lgkmcnt(8)
	v_mov_b32_e32 v40, v14
	v_mov_b32_e32 v41, v6
	v_pk_add_f32 v[0:1], v[0:1], v[2:3]
	v_mov_b32_e32 v4, v13
	v_pk_add_f32 v[38:39], v[38:39], v[40:41]
	s_waitcnt lgkmcnt(3)
	v_mov_b32_e32 v40, v24
	v_mov_b32_e32 v41, v16
	v_pk_add_f32 v[0:1], v[0:1], v[4:5]
	v_mov_b32_e32 v6, v15
	v_pk_add_f32 v[38:39], v[38:39], v[40:41]
	s_waitcnt lgkmcnt(2)
	v_mov_b32_e32 v40, v26
	v_mov_b32_e32 v41, v18
	v_pk_add_f32 v[0:1], v[0:1], v[6:7]
	v_mov_b32_e32 v16, v25
	v_pk_add_f32 v[38:39], v[38:39], v[40:41]
	s_waitcnt lgkmcnt(1)
	v_mov_b32_e32 v40, v28
	v_mov_b32_e32 v41, v20
	v_pk_add_f32 v[0:1], v[0:1], v[16:17]
	v_mov_b32_e32 v18, v27
	v_pk_add_f32 v[38:39], v[38:39], v[40:41]
	s_waitcnt lgkmcnt(0)
	v_mov_b32_e32 v40, v30
	v_mov_b32_e32 v41, v22
	v_pk_add_f32 v[0:1], v[0:1], v[18:19]
	v_mov_b32_e32 v20, v29
	v_pk_add_f32 v[38:39], v[38:39], v[40:41]
	v_pk_add_f32 v[0:1], v[0:1], v[20:21]
	v_mov_b32_e32 v22, v31
	v_pk_add_f32 v[0:1], v[0:1], v[22:23]
	v_mul_f32_e32 v2, 0xbfb8aa3b, v39
	v_exp_f32_e32 v2, v2
	v_mul_f32_e32 v3, 0xbfb8aa3b, v1
	v_exp_f32_e32 v3, v3
	s_lshl_b32 s0, s20, 3
	v_add_f32_e32 v2, 1.0, v2
	v_rcp_f32_e32 v4, v2
	v_add_f32_e32 v2, 1.0, v3
	v_rcp_f32_e32 v3, v2
	s_andn2_b32 s0, s0, 31
	v_mul_f32_e32 v4, v39, v4
	v_mul_f32_e32 v4, v38, v4
	v_mul_f32_e32 v1, v1, v3
	v_mul_f32_e32 v0, v0, v1
	v_cvt_pk_bf16_f32 v4, v4, v0
	v_mov_b64_e32 v[0:1], s[10:11]
	v_add_u32_e32 v2, s0, v43
	v_mad_u64_u32 v[0:1], s[0:1], v36, s16, v[0:1]
	s_add_i32 s0, s19, 1
	s_add_i32 s83, s83, s70
	s_add_i32 s18, s18, s46
	s_add_i32 s17, s17, s71
	v_ashrrev_i32_e32 v3, 31, v2
	s_cmp_gt_u32 s19, 2
	v_lshl_add_u64 v[0:1], v[2:3], 1, v[0:1]
	s_cselect_b64 s[12:13], -1, 0
	s_mov_b32 s19, s0
	global_store_dword v[0:1], v4, off
	s_branch .LBB0_1126
